# K-loop MFMA segments: the two k-steps of each accumulator issued back to back (26 of 32 segments)
# speedup vs baseline: 1.0083x; 1.0083x over previous
.LBB0_1232:
	ds_read_b128 v[106:109], v197
	ds_read_b128 v[114:117], v197 offset:1024
	ds_read_b128 v[122:125], v197 offset:2048
	ds_read_b128 v[130:133], v197 offset:3072
	ds_read_b128 v[146:149], v201
	ds_read_b128 v[150:153], v201 offset:1024
	ds_read_b128 v[154:157], v201 offset:2048
	ds_read_b128 v[158:161], v201 offset:3072
	s_add_u32 s30, s28, 0xfff80080
	s_addc_u32 s31, s29, -1
	s_cmp_eq_u32 s70, 28
	s_cselect_b32 s35, s23, s31
	s_cselect_b32 s34, s66, s30
	s_cselect_b32 s31, s15, s69
	s_cselect_b32 s30, s67, s68
	v_lshl_add_u64 v[194:195], s[28:29], 0, v[174:175]
	s_add_i32 m0, s19, 0xc000
	ds_read_b128 v[162:165], v204
	ds_read_b128 v[182:185], v204 offset:1024
	ds_read_b128 v[186:189], v204 offset:2048
	ds_read_b128 v[206:209], v204 offset:3072
	ds_read_b128 v[210:213], v204 offset:4096
	ds_read_b128 v[214:217], v204 offset:5120
	ds_read_b128 v[218:221], v204 offset:6144
	ds_read_b128 v[222:225], v204 offset:7168
	global_load_lds_dwordx4 v[194:195], off
	v_lshl_add_u64 v[194:195], s[28:29], 0, v[176:177]
	s_add_i32 m0, s19, 0xe000
	s_nop 0
	global_load_lds_dwordx4 v[194:195], off
	s_waitcnt vmcnt(8)
	s_waitcnt lgkmcnt(0)
	s_barrier
	s_waitcnt lgkmcnt(0)
	v_mfma_i32_16x16x64_i8 v[142:145], v[106:109], v[162:165], v[142:145]
	v_mfma_i32_16x16x64_i8 v[142:145], v[114:117], v[182:185], v[142:145]
	v_mfma_i32_16x16x64_i8 v[138:141], v[122:125], v[162:165], v[138:141]
	v_mfma_i32_16x16x64_i8 v[138:141], v[130:133], v[182:185], v[138:141]
	v_mfma_i32_16x16x64_i8 v[118:121], v[106:109], v[186:189], v[118:121]
	v_mfma_i32_16x16x64_i8 v[118:121], v[114:117], v[206:209], v[118:121]
	v_mfma_i32_16x16x64_i8 v[110:113], v[122:125], v[186:189], v[110:113]
	v_mfma_i32_16x16x64_i8 v[110:113], v[130:133], v[206:209], v[110:113]
	v_mfma_i32_16x16x64_i8 v[94:97], v[106:109], v[210:213], v[94:97]
	v_mfma_i32_16x16x64_i8 v[94:97], v[114:117], v[214:217], v[94:97]
	v_mfma_i32_16x16x64_i8 v[90:93], v[122:125], v[210:213], v[90:93]
	v_mfma_i32_16x16x64_i8 v[90:93], v[130:133], v[214:217], v[90:93]
	v_mfma_i32_16x16x64_i8 v[78:81], v[106:109], v[218:221], v[78:81]
	v_mfma_i32_16x16x64_i8 v[78:81], v[114:117], v[222:225], v[78:81]
	v_mfma_i32_16x16x64_i8 v[74:77], v[122:125], v[218:221], v[74:77]
	v_mfma_i32_16x16x64_i8 v[74:77], v[130:133], v[222:225], v[74:77]
	v_mfma_i32_16x16x64_i8 v[134:137], v[146:149], v[162:165], v[134:137]
	v_mfma_i32_16x16x64_i8 v[134:137], v[150:153], v[182:185], v[134:137]
	v_mfma_i32_16x16x64_i8 v[126:129], v[154:157], v[162:165], v[126:129]
	v_mfma_i32_16x16x64_i8 v[126:129], v[158:161], v[182:185], v[126:129]
	v_mfma_i32_16x16x64_i8 v[102:105], v[146:149], v[186:189], v[102:105]
	v_mfma_i32_16x16x64_i8 v[102:105], v[150:153], v[206:209], v[102:105]
	v_mfma_i32_16x16x64_i8 v[98:101], v[154:157], v[186:189], v[98:101]
	v_mfma_i32_16x16x64_i8 v[98:101], v[158:161], v[206:209], v[98:101]
	v_mfma_i32_16x16x64_i8 v[86:89], v[146:149], v[210:213], v[86:89]
	v_mfma_i32_16x16x64_i8 v[86:89], v[150:153], v[214:217], v[86:89]
	v_mfma_i32_16x16x64_i8 v[82:85], v[154:157], v[210:213], v[82:85]
	v_mfma_i32_16x16x64_i8 v[82:85], v[158:161], v[214:217], v[82:85]
	v_mfma_i32_16x16x64_i8 v[70:73], v[146:149], v[218:221], v[70:73]
	v_mfma_i32_16x16x64_i8 v[70:73], v[150:153], v[222:225], v[70:73]
	v_mfma_i32_16x16x64_i8 v[66:69], v[154:157], v[218:221], v[66:69]
	v_mfma_i32_16x16x64_i8 v[66:69], v[158:161], v[222:225], v[66:69]
	s_barrier
	s_add_i32 s71, s63, s39
	v_lshl_add_u64 v[194:195], s[30:31], 0, v[168:169]
	s_mov_b32 m0, s71
	ds_read_b128 v[162:165], v204 offset:16384
	ds_read_b128 v[182:185], v204 offset:17408
	ds_read_b128 v[186:189], v204 offset:18432
	ds_read_b128 v[206:209], v204 offset:19456
	ds_read_b128 v[210:213], v204 offset:20480
	ds_read_b128 v[214:217], v204 offset:21504
	ds_read_b128 v[218:221], v204 offset:22528
	ds_read_b128 v[222:225], v204 offset:23552
	global_load_lds_dwordx4 v[194:195], off
	s_add_i32 m0, s71, 0x2000
	s_add_u32 s72, s30, 0x80000
	v_lshl_add_u64 v[198:199], s[30:31], 0, v[172:173]
	s_addc_u32 s73, s31, 0
	s_add_i32 s71, s64, s39
	global_load_lds_dwordx4 v[198:199], off
	v_lshl_add_u64 v[202:203], s[72:73], 0, v[168:169]
	s_mov_b32 m0, s71
	v_lshl_add_u64 v[226:227], s[34:35], 0, v[170:171]
	global_load_lds_dwordx4 v[202:203], off
	v_lshl_add_u64 v[202:203], s[72:73], 0, v[172:173]
	s_add_i32 m0, s71, 0x2000
	s_nop 0
	global_load_lds_dwordx4 v[202:203], off
	v_lshl_add_u64 v[202:203], s[34:35], 0, v[166:167]
	s_mov_b32 m0, s19
	s_nop 0
	global_load_lds_dwordx4 v[202:203], off
	s_mov_b32 m0, s40
	s_nop 0
	global_load_lds_dwordx4 v[226:227], off
	s_waitcnt vmcnt(8)
	s_waitcnt lgkmcnt(0)
	s_barrier
	s_waitcnt lgkmcnt(0)
	v_mfma_i32_16x16x64_i8 v[62:65], v[106:109], v[162:165], v[62:65]
	v_mfma_i32_16x16x64_i8 v[62:65], v[114:117], v[182:185], v[62:65]
	v_mfma_i32_16x16x64_i8 v[58:61], v[122:125], v[162:165], v[58:61]
	v_mfma_i32_16x16x64_i8 v[58:61], v[130:133], v[182:185], v[58:61]
	v_mfma_i32_16x16x64_i8 v[46:49], v[106:109], v[186:189], v[46:49]
	v_mfma_i32_16x16x64_i8 v[46:49], v[114:117], v[206:209], v[46:49]
	v_mfma_i32_16x16x64_i8 v[42:45], v[122:125], v[186:189], v[42:45]
	v_mfma_i32_16x16x64_i8 v[42:45], v[130:133], v[206:209], v[42:45]
	v_mfma_i32_16x16x64_i8 v[30:33], v[106:109], v[210:213], v[30:33]
	v_mfma_i32_16x16x64_i8 v[30:33], v[114:117], v[214:217], v[30:33]
	v_mfma_i32_16x16x64_i8 v[26:29], v[122:125], v[210:213], v[26:29]
	v_mfma_i32_16x16x64_i8 v[26:29], v[130:133], v[214:217], v[26:29]
	v_mfma_i32_16x16x64_i8 v[14:17], v[106:109], v[218:221], v[14:17]
	v_mfma_i32_16x16x64_i8 v[14:17], v[114:117], v[222:225], v[14:17]
	v_mfma_i32_16x16x64_i8 v[10:13], v[122:125], v[218:221], v[10:13]
	v_mfma_i32_16x16x64_i8 v[10:13], v[130:133], v[222:225], v[10:13]
	v_mfma_i32_16x16x64_i8 v[54:57], v[146:149], v[162:165], v[54:57]
	v_mfma_i32_16x16x64_i8 v[54:57], v[150:153], v[182:185], v[54:57]
	v_mfma_i32_16x16x64_i8 v[50:53], v[154:157], v[162:165], v[50:53]
	v_mfma_i32_16x16x64_i8 v[50:53], v[158:161], v[182:185], v[50:53]
	v_mfma_i32_16x16x64_i8 v[38:41], v[146:149], v[186:189], v[38:41]
	v_mfma_i32_16x16x64_i8 v[38:41], v[150:153], v[206:209], v[38:41]
	v_mfma_i32_16x16x64_i8 v[34:37], v[154:157], v[186:189], v[34:37]
	v_mfma_i32_16x16x64_i8 v[34:37], v[158:161], v[206:209], v[34:37]
	v_mfma_i32_16x16x64_i8 v[22:25], v[146:149], v[210:213], v[22:25]
	v_mfma_i32_16x16x64_i8 v[22:25], v[150:153], v[214:217], v[22:25]
	v_mfma_i32_16x16x64_i8 v[18:21], v[154:157], v[210:213], v[18:21]
	v_mfma_i32_16x16x64_i8 v[18:21], v[158:161], v[214:217], v[18:21]
	v_mfma_i32_16x16x64_i8 v[6:9], v[146:149], v[218:221], v[6:9]
	v_mfma_i32_16x16x64_i8 v[6:9], v[150:153], v[222:225], v[6:9]
	v_mfma_i32_16x16x64_i8 v[2:5], v[154:157], v[218:221], v[2:5]
	v_mfma_i32_16x16x64_i8 v[2:5], v[158:161], v[222:225], v[2:5]
	s_barrier
	s_add_i32 s71, 0, 0x18000
	s_add_i32 s72, 0, 0x1c000
	v_add_u32_e32 v130, s71, v193
	v_add_u32_e32 v158, s72, v193
	ds_read_b128 v[106:109], v130
	ds_read_b128 v[114:117], v130 offset:1024
	ds_read_b128 v[122:125], v130 offset:2048
	ds_read_b128 v[130:133], v130 offset:3072
	ds_read_b128 v[146:149], v158
	ds_read_b128 v[150:153], v158 offset:1024
	ds_read_b128 v[154:157], v158 offset:2048
	ds_read_b128 v[158:161], v158 offset:3072
	s_add_u32 s34, s34, 0x80000
	s_addc_u32 s35, s35, 0
	s_mov_b32 m0, s41
	v_lshl_add_u64 v[228:229], s[34:35], 0, v[166:167]
	ds_read_b128 v[162:165], v204 offset:32768
	ds_read_b128 v[182:185], v204 offset:33792
	ds_read_b128 v[186:189], v204 offset:34816
	ds_read_b128 v[206:209], v204 offset:35840
	ds_read_b128 v[210:213], v204 offset:36864
	ds_read_b128 v[214:217], v204 offset:37888
	ds_read_b128 v[218:221], v204 offset:38912
	ds_read_b128 v[222:225], v204 offset:39936
	global_load_lds_dwordx4 v[228:229], off
	v_lshl_add_u64 v[228:229], s[34:35], 0, v[170:171]
	s_mov_b32 m0, s42
	s_nop 0
	global_load_lds_dwordx4 v[228:229], off
	s_waitcnt vmcnt(8)
	s_waitcnt lgkmcnt(0)
	s_barrier
	s_waitcnt lgkmcnt(0)
	v_mfma_i32_16x16x64_i8 v[142:145], v[106:109], v[162:165], v[142:145]
	v_mfma_i32_16x16x64_i8 v[142:145], v[114:117], v[182:185], v[142:145]
	v_mfma_i32_16x16x64_i8 v[138:141], v[122:125], v[162:165], v[138:141]
	v_mfma_i32_16x16x64_i8 v[138:141], v[130:133], v[182:185], v[138:141]
	v_mfma_i32_16x16x64_i8 v[118:121], v[106:109], v[186:189], v[118:121]
	v_mfma_i32_16x16x64_i8 v[118:121], v[114:117], v[206:209], v[118:121]
	v_mfma_i32_16x16x64_i8 v[110:113], v[122:125], v[186:189], v[110:113]
	v_mfma_i32_16x16x64_i8 v[110:113], v[130:133], v[206:209], v[110:113]
	v_mfma_i32_16x16x64_i8 v[94:97], v[106:109], v[210:213], v[94:97]
	v_mfma_i32_16x16x64_i8 v[94:97], v[114:117], v[214:217], v[94:97]
	v_mfma_i32_16x16x64_i8 v[90:93], v[122:125], v[210:213], v[90:93]
	v_mfma_i32_16x16x64_i8 v[90:93], v[130:133], v[214:217], v[90:93]
	v_mfma_i32_16x16x64_i8 v[78:81], v[106:109], v[218:221], v[78:81]
	v_mfma_i32_16x16x64_i8 v[78:81], v[114:117], v[222:225], v[78:81]
	v_mfma_i32_16x16x64_i8 v[74:77], v[122:125], v[218:221], v[74:77]
	v_mfma_i32_16x16x64_i8 v[74:77], v[130:133], v[222:225], v[74:77]
	v_mfma_i32_16x16x64_i8 v[134:137], v[146:149], v[162:165], v[134:137]
	v_mfma_i32_16x16x64_i8 v[134:137], v[150:153], v[182:185], v[134:137]
	v_mfma_i32_16x16x64_i8 v[126:129], v[154:157], v[162:165], v[126:129]
	v_mfma_i32_16x16x64_i8 v[126:129], v[158:161], v[182:185], v[126:129]
	v_mfma_i32_16x16x64_i8 v[102:105], v[146:149], v[186:189], v[102:105]
	v_mfma_i32_16x16x64_i8 v[102:105], v[150:153], v[206:209], v[102:105]
	v_mfma_i32_16x16x64_i8 v[98:101], v[154:157], v[186:189], v[98:101]
	v_mfma_i32_16x16x64_i8 v[98:101], v[158:161], v[206:209], v[98:101]
	v_mfma_i32_16x16x64_i8 v[86:89], v[146:149], v[210:213], v[86:89]
	v_mfma_i32_16x16x64_i8 v[86:89], v[150:153], v[214:217], v[86:89]
	v_mfma_i32_16x16x64_i8 v[82:85], v[154:157], v[210:213], v[82:85]
	v_mfma_i32_16x16x64_i8 v[82:85], v[158:161], v[214:217], v[82:85]
	v_mfma_i32_16x16x64_i8 v[70:73], v[146:149], v[218:221], v[70:73]
	v_mfma_i32_16x16x64_i8 v[70:73], v[150:153], v[222:225], v[70:73]
	v_mfma_i32_16x16x64_i8 v[66:69], v[154:157], v[218:221], v[66:69]
	v_mfma_i32_16x16x64_i8 v[66:69], v[158:161], v[222:225], v[66:69]
	s_barrier
	s_add_i32 s34, s71, s39
	v_lshl_add_u64 v[194:195], v[194:195], 0, s[10:11]
	s_mov_b32 m0, s34
	ds_read_b128 v[162:165], v204 offset:49152
	ds_read_b128 v[182:185], v204 offset:50176
	ds_read_b128 v[186:189], v204 offset:51200
	ds_read_b128 v[206:209], v204 offset:52224
	ds_read_b128 v[210:213], v204 offset:53248
	ds_read_b128 v[214:217], v204 offset:54272
	ds_read_b128 v[218:221], v204 offset:55296
	ds_read_b128 v[222:225], v204 offset:56320
	global_load_lds_dwordx4 v[194:195], off
	s_add_i32 m0, s34, 0x2000
	s_add_u32 s30, s30, 0x80080
	v_lshl_add_u64 v[194:195], v[198:199], 0, s[10:11]
	s_addc_u32 s31, s31, 0
	s_add_i32 s34, s72, s39
	global_load_lds_dwordx4 v[194:195], off
	v_lshl_add_u64 v[194:195], s[30:31], 0, v[168:169]
	s_mov_b32 m0, s34
	s_nop 0
	global_load_lds_dwordx4 v[194:195], off
	v_lshl_add_u64 v[194:195], s[30:31], 0, v[172:173]
	s_add_i32 m0, s34, 0x2000
	s_nop 0
	global_load_lds_dwordx4 v[194:195], off
	v_lshl_add_u64 v[194:195], v[202:203], 0, s[10:11]
	s_mov_b32 m0, s60
	s_nop 0
	global_load_lds_dwordx4 v[194:195], off
	v_lshl_add_u64 v[194:195], v[226:227], 0, s[10:11]
	s_mov_b32 m0, s61
	s_nop 0
	global_load_lds_dwordx4 v[194:195], off
	s_waitcnt vmcnt(8)
	s_waitcnt lgkmcnt(0)
	s_barrier
	s_waitcnt lgkmcnt(0)
	v_mfma_i32_16x16x64_i8 v[62:65], v[106:109], v[162:165], v[62:65]
	v_mfma_i32_16x16x64_i8 v[62:65], v[114:117], v[182:185], v[62:65]
	v_mfma_i32_16x16x64_i8 v[58:61], v[122:125], v[162:165], v[58:61]
	v_mfma_i32_16x16x64_i8 v[58:61], v[130:133], v[182:185], v[58:61]
	v_mfma_i32_16x16x64_i8 v[46:49], v[106:109], v[186:189], v[46:49]
	v_mfma_i32_16x16x64_i8 v[46:49], v[114:117], v[206:209], v[46:49]
	v_mfma_i32_16x16x64_i8 v[42:45], v[122:125], v[186:189], v[42:45]
	v_mfma_i32_16x16x64_i8 v[42:45], v[130:133], v[206:209], v[42:45]
	v_mfma_i32_16x16x64_i8 v[30:33], v[106:109], v[210:213], v[30:33]
	v_mfma_i32_16x16x64_i8 v[30:33], v[114:117], v[214:217], v[30:33]
	v_mfma_i32_16x16x64_i8 v[26:29], v[122:125], v[210:213], v[26:29]
	v_mfma_i32_16x16x64_i8 v[26:29], v[130:133], v[214:217], v[26:29]
	v_mfma_i32_16x16x64_i8 v[14:17], v[106:109], v[218:221], v[14:17]
	v_mfma_i32_16x16x64_i8 v[14:17], v[114:117], v[222:225], v[14:17]
	v_mfma_i32_16x16x64_i8 v[10:13], v[122:125], v[218:221], v[10:13]
	v_mfma_i32_16x16x64_i8 v[10:13], v[130:133], v[222:225], v[10:13]
	v_mfma_i32_16x16x64_i8 v[54:57], v[146:149], v[162:165], v[54:57]
	v_mfma_i32_16x16x64_i8 v[54:57], v[150:153], v[182:185], v[54:57]
	v_mfma_i32_16x16x64_i8 v[50:53], v[154:157], v[162:165], v[50:53]
	v_mfma_i32_16x16x64_i8 v[50:53], v[158:161], v[182:185], v[50:53]
	v_mfma_i32_16x16x64_i8 v[38:41], v[146:149], v[186:189], v[38:41]
	v_mfma_i32_16x16x64_i8 v[38:41], v[150:153], v[206:209], v[38:41]
	v_mfma_i32_16x16x64_i8 v[34:37], v[154:157], v[186:189], v[34:37]
	v_mfma_i32_16x16x64_i8 v[34:37], v[158:161], v[206:209], v[34:37]
	v_mfma_i32_16x16x64_i8 v[22:25], v[146:149], v[210:213], v[22:25]
	v_mfma_i32_16x16x64_i8 v[22:25], v[150:153], v[214:217], v[22:25]
	v_mfma_i32_16x16x64_i8 v[18:21], v[154:157], v[210:213], v[18:21]
	v_mfma_i32_16x16x64_i8 v[18:21], v[158:161], v[214:217], v[18:21]
	v_mfma_i32_16x16x64_i8 v[6:9], v[146:149], v[218:221], v[6:9]
	v_mfma_i32_16x16x64_i8 v[6:9], v[150:153], v[222:225], v[6:9]
	v_mfma_i32_16x16x64_i8 v[2:5], v[154:157], v[218:221], v[2:5]
	v_mfma_i32_16x16x64_i8 v[2:5], v[158:161], v[222:225], v[2:5]
	s_barrier
	s_add_i32 s70, s70, 2
	s_add_u32 s28, s28, 0x100
	s_addc_u32 s29, s29, 0
	s_add_u32 s68, s68, 0x100
	s_addc_u32 s69, s69, 0
	s_cmp_gt_u32 s70, 29
	s_cbranch_scc0 .LBB0_1232
	s_and_b64 vcc, exec, s[12:13]
	s_cbranch_vccz .LBB0_1235
	s_barrier

.LBB0_1367:
	ds_read_b128 v[130:133], v234
	ds_read_b128 v[134:137], v234 offset:1024
	ds_read_b128 v[162:165], v234 offset:2048
	ds_read_b128 v[166:169], v234 offset:3072
	ds_read_b128 v[170:173], v235
	ds_read_b128 v[174:177], v235 offset:1024
	ds_read_b128 v[178:181], v235 offset:2048
	ds_read_b128 v[182:185], v235 offset:3072
	s_add_u32 s6, s4, 0x100
	s_addc_u32 s7, s5, 0
	s_cmp_eq_u32 s80, 28
	s_cselect_b32 s57, s35, s7
	s_cselect_b32 s56, s43, s6
	s_cselect_b32 s19, s31, s79
	s_cselect_b32 s18, vcc_lo, vcc_hi
	v_lshl_add_u64 v[218:219], s[4:5], 0, v[154:155]
	s_add_i32 m0, s65, 0xc000
	ds_read_b128 v[186:189], v236
	ds_read_b128 v[190:193], v236 offset:1024
	ds_read_b128 v[194:197], v236 offset:2048
	ds_read_b128 v[198:201], v236 offset:3072
	ds_read_b128 v[202:205], v236 offset:4096
	ds_read_b128 v[206:209], v236 offset:5120
	ds_read_b128 v[210:213], v236 offset:6144
	ds_read_b128 v[214:217], v236 offset:7168
	global_load_lds_dwordx4 v[218:219], off
	v_lshl_add_u64 v[218:219], s[4:5], 0, v[156:157]
	s_add_i32 m0, s65, 0xe000
	s_nop 0
	global_load_lds_dwordx4 v[218:219], off
	s_waitcnt vmcnt(8)
	s_waitcnt lgkmcnt(0)
	s_barrier
	s_waitcnt lgkmcnt(0)
	v_mfma_i32_16x16x64_i8 v[118:121], v[130:133], v[186:189], v[118:121]
	v_mfma_i32_16x16x64_i8 v[118:121], v[134:137], v[190:193], v[118:121]
	v_mfma_i32_16x16x64_i8 v[102:105], v[162:165], v[186:189], v[102:105]
	v_mfma_i32_16x16x64_i8 v[102:105], v[166:169], v[190:193], v[102:105]
	v_mfma_i32_16x16x64_i8 v[114:117], v[130:133], v[194:197], v[114:117]
	v_mfma_i32_16x16x64_i8 v[114:117], v[134:137], v[198:201], v[114:117]
	v_mfma_i32_16x16x64_i8 v[98:101], v[162:165], v[194:197], v[98:101]
	v_mfma_i32_16x16x64_i8 v[98:101], v[166:169], v[198:201], v[98:101]
	v_mfma_i32_16x16x64_i8 v[126:129], v[130:133], v[202:205], v[126:129]
	v_mfma_i32_16x16x64_i8 v[126:129], v[134:137], v[206:209], v[126:129]
	v_mfma_i32_16x16x64_i8 v[110:113], v[162:165], v[202:205], v[110:113]
	v_mfma_i32_16x16x64_i8 v[110:113], v[166:169], v[206:209], v[110:113]
	v_mfma_i32_16x16x64_i8 v[122:125], v[130:133], v[210:213], v[122:125]
	v_mfma_i32_16x16x64_i8 v[122:125], v[134:137], v[214:217], v[122:125]
	v_mfma_i32_16x16x64_i8 v[106:109], v[162:165], v[210:213], v[106:109]
	v_mfma_i32_16x16x64_i8 v[106:109], v[166:169], v[214:217], v[106:109]
	v_mfma_i32_16x16x64_i8 v[86:89], v[170:173], v[186:189], v[86:89]
	v_mfma_i32_16x16x64_i8 v[86:89], v[174:177], v[190:193], v[86:89]
	v_mfma_i32_16x16x64_i8 v[70:73], v[178:181], v[186:189], v[70:73]
	v_mfma_i32_16x16x64_i8 v[70:73], v[182:185], v[190:193], v[70:73]
	v_mfma_i32_16x16x64_i8 v[82:85], v[170:173], v[194:197], v[82:85]
	v_mfma_i32_16x16x64_i8 v[82:85], v[174:177], v[198:201], v[82:85]
	v_mfma_i32_16x16x64_i8 v[66:69], v[178:181], v[194:197], v[66:69]
	v_mfma_i32_16x16x64_i8 v[66:69], v[182:185], v[198:201], v[66:69]
	v_mfma_i32_16x16x64_i8 v[94:97], v[170:173], v[202:205], v[94:97]
	v_mfma_i32_16x16x64_i8 v[94:97], v[174:177], v[206:209], v[94:97]
	v_mfma_i32_16x16x64_i8 v[78:81], v[178:181], v[202:205], v[78:81]
	v_mfma_i32_16x16x64_i8 v[78:81], v[182:185], v[206:209], v[78:81]
	v_mfma_i32_16x16x64_i8 v[90:93], v[170:173], v[210:213], v[90:93]
	v_mfma_i32_16x16x64_i8 v[90:93], v[174:177], v[214:217], v[90:93]
	v_mfma_i32_16x16x64_i8 v[74:77], v[178:181], v[210:213], v[74:77]
	v_mfma_i32_16x16x64_i8 v[74:77], v[182:185], v[214:217], v[74:77]
	s_barrier
	s_add_i32 s4, s97, s63
	v_lshl_add_u64 v[218:219], s[18:19], 0, v[144:145]
	s_mov_b32 m0, s4
	ds_read_b128 v[186:189], v236 offset:16384
	ds_read_b128 v[190:193], v236 offset:17408
	ds_read_b128 v[194:197], v236 offset:18432
	ds_read_b128 v[198:201], v236 offset:19456
	ds_read_b128 v[202:205], v236 offset:20480
	ds_read_b128 v[206:209], v236 offset:21504
	ds_read_b128 v[210:213], v236 offset:22528
	ds_read_b128 v[214:217], v236 offset:23552
	global_load_lds_dwordx4 v[218:219], off
	s_add_i32 m0, s4, 0x2000
	s_add_u32 s4, s18, 0x80000
	v_lshl_add_u64 v[220:221], s[18:19], 0, v[148:149]
	s_addc_u32 s5, s19, 0
	s_add_i32 s81, s0, s63
	global_load_lds_dwordx4 v[220:221], off
	v_lshl_add_u64 v[222:223], s[4:5], 0, v[144:145]
	s_mov_b32 m0, s81
	v_lshl_add_u64 v[224:225], s[56:57], 0, v[146:147]
	global_load_lds_dwordx4 v[222:223], off
	v_lshl_add_u64 v[222:223], s[4:5], 0, v[148:149]
	s_add_i32 m0, s81, 0x2000
	s_nop 0
	global_load_lds_dwordx4 v[222:223], off
	v_lshl_add_u64 v[222:223], s[56:57], 0, v[142:143]
	s_mov_b32 m0, s65
	s_nop 0
	global_load_lds_dwordx4 v[222:223], off
	s_mov_b32 m0, s66
	s_nop 0
	global_load_lds_dwordx4 v[224:225], off
	s_waitcnt vmcnt(8)
	s_waitcnt lgkmcnt(0)
	s_barrier
	s_waitcnt lgkmcnt(0)
	v_mfma_i32_16x16x64_i8 v[54:57], v[130:133], v[186:189], v[54:57]
	v_mfma_i32_16x16x64_i8 v[54:57], v[134:137], v[190:193], v[54:57]
	v_mfma_i32_16x16x64_i8 v[18:21], v[162:165], v[186:189], v[18:21]
	v_mfma_i32_16x16x64_i8 v[18:21], v[166:169], v[190:193], v[18:21]
	v_mfma_i32_16x16x64_i8 v[50:53], v[130:133], v[194:197], v[50:53]
	v_mfma_i32_16x16x64_i8 v[50:53], v[134:137], v[198:201], v[50:53]
	v_mfma_i32_16x16x64_i8 v[22:25], v[162:165], v[194:197], v[22:25]
	v_mfma_i32_16x16x64_i8 v[22:25], v[166:169], v[198:201], v[22:25]
	v_mfma_i32_16x16x64_i8 v[62:65], v[130:133], v[202:205], v[62:65]
	v_mfma_i32_16x16x64_i8 v[62:65], v[134:137], v[206:209], v[62:65]
	v_mfma_i32_16x16x64_i8 v[30:33], v[162:165], v[202:205], v[30:33]
	v_mfma_i32_16x16x64_i8 v[30:33], v[166:169], v[206:209], v[30:33]
	v_mfma_i32_16x16x64_i8 v[58:61], v[130:133], v[210:213], v[58:61]
	v_mfma_i32_16x16x64_i8 v[58:61], v[134:137], v[214:217], v[58:61]
	v_mfma_i32_16x16x64_i8 v[26:29], v[162:165], v[210:213], v[26:29]
	v_mfma_i32_16x16x64_i8 v[26:29], v[166:169], v[214:217], v[26:29]
	v_mfma_i32_16x16x64_i8 v[46:49], v[170:173], v[186:189], v[46:49]
	v_mfma_i32_16x16x64_i8 v[46:49], v[174:177], v[190:193], v[46:49]
	v_mfma_i32_16x16x64_i8 v[14:17], v[178:181], v[186:189], v[14:17]
	v_mfma_i32_16x16x64_i8 v[14:17], v[182:185], v[190:193], v[14:17]
	v_mfma_i32_16x16x64_i8 v[42:45], v[170:173], v[194:197], v[42:45]
	v_mfma_i32_16x16x64_i8 v[42:45], v[174:177], v[198:201], v[42:45]
	v_mfma_i32_16x16x64_i8 v[10:13], v[178:181], v[194:197], v[10:13]
	v_mfma_i32_16x16x64_i8 v[10:13], v[182:185], v[198:201], v[10:13]
	v_mfma_i32_16x16x64_i8 v[38:41], v[170:173], v[202:205], v[38:41]
	v_mfma_i32_16x16x64_i8 v[38:41], v[174:177], v[206:209], v[38:41]
	v_mfma_i32_16x16x64_i8 v[6:9], v[178:181], v[202:205], v[6:9]
	v_mfma_i32_16x16x64_i8 v[6:9], v[182:185], v[206:209], v[6:9]
	v_mfma_i32_16x16x64_i8 v[34:37], v[170:173], v[210:213], v[34:37]
	v_mfma_i32_16x16x64_i8 v[34:37], v[174:177], v[214:217], v[34:37]
	v_mfma_i32_16x16x64_i8 v[2:5], v[178:181], v[210:213], v[2:5]
	v_mfma_i32_16x16x64_i8 v[2:5], v[182:185], v[214:217], v[2:5]
	s_barrier
	s_add_i32 s81, 0, 0x18000
	s_add_i32 s82, 0, 0x1c000
	v_add_u32_e32 v166, s81, v232
	v_add_u32_e32 v182, s82, v232
	ds_read_b128 v[130:133], v166
	ds_read_b128 v[134:137], v166 offset:1024
	ds_read_b128 v[162:165], v166 offset:2048
	ds_read_b128 v[166:169], v166 offset:3072
	ds_read_b128 v[170:173], v182
	ds_read_b128 v[174:177], v182 offset:1024
	ds_read_b128 v[178:181], v182 offset:2048
	ds_read_b128 v[182:185], v182 offset:3072
	s_add_u32 s4, s56, 0x80000
	s_addc_u32 s5, s57, 0
	s_mov_b32 m0, s67
	v_lshl_add_u64 v[226:227], s[4:5], 0, v[142:143]
	ds_read_b128 v[186:189], v236 offset:32768
	ds_read_b128 v[190:193], v236 offset:33792
	ds_read_b128 v[194:197], v236 offset:34816
	ds_read_b128 v[198:201], v236 offset:35840
	ds_read_b128 v[202:205], v236 offset:36864
	ds_read_b128 v[206:209], v236 offset:37888
	ds_read_b128 v[210:213], v236 offset:38912
	ds_read_b128 v[214:217], v236 offset:39936
	global_load_lds_dwordx4 v[226:227], off
	v_lshl_add_u64 v[226:227], s[4:5], 0, v[146:147]
	s_mov_b32 m0, s68
	s_nop 0
	global_load_lds_dwordx4 v[226:227], off
	s_waitcnt vmcnt(8)
	s_waitcnt lgkmcnt(0)
	s_barrier
	s_waitcnt lgkmcnt(0)
	v_mfma_i32_16x16x64_i8 v[118:121], v[130:133], v[186:189], v[118:121]
	v_mfma_i32_16x16x64_i8 v[118:121], v[134:137], v[190:193], v[118:121]
	v_mfma_i32_16x16x64_i8 v[102:105], v[162:165], v[186:189], v[102:105]
	v_mfma_i32_16x16x64_i8 v[102:105], v[166:169], v[190:193], v[102:105]
	v_mfma_i32_16x16x64_i8 v[114:117], v[130:133], v[194:197], v[114:117]
	v_mfma_i32_16x16x64_i8 v[114:117], v[134:137], v[198:201], v[114:117]
	v_mfma_i32_16x16x64_i8 v[98:101], v[162:165], v[194:197], v[98:101]
	v_mfma_i32_16x16x64_i8 v[98:101], v[166:169], v[198:201], v[98:101]
	v_mfma_i32_16x16x64_i8 v[126:129], v[130:133], v[202:205], v[126:129]
	v_mfma_i32_16x16x64_i8 v[126:129], v[134:137], v[206:209], v[126:129]
	v_mfma_i32_16x16x64_i8 v[110:113], v[162:165], v[202:205], v[110:113]
	v_mfma_i32_16x16x64_i8 v[110:113], v[166:169], v[206:209], v[110:113]
	v_mfma_i32_16x16x64_i8 v[122:125], v[130:133], v[210:213], v[122:125]
	v_mfma_i32_16x16x64_i8 v[122:125], v[134:137], v[214:217], v[122:125]
	v_mfma_i32_16x16x64_i8 v[106:109], v[162:165], v[210:213], v[106:109]
	v_mfma_i32_16x16x64_i8 v[106:109], v[166:169], v[214:217], v[106:109]
	v_mfma_i32_16x16x64_i8 v[86:89], v[170:173], v[186:189], v[86:89]
	v_mfma_i32_16x16x64_i8 v[86:89], v[174:177], v[190:193], v[86:89]
	v_mfma_i32_16x16x64_i8 v[70:73], v[178:181], v[186:189], v[70:73]
	v_mfma_i32_16x16x64_i8 v[70:73], v[182:185], v[190:193], v[70:73]
	v_mfma_i32_16x16x64_i8 v[82:85], v[170:173], v[194:197], v[82:85]
	v_mfma_i32_16x16x64_i8 v[82:85], v[174:177], v[198:201], v[82:85]
	v_mfma_i32_16x16x64_i8 v[66:69], v[178:181], v[194:197], v[66:69]
	v_mfma_i32_16x16x64_i8 v[66:69], v[182:185], v[198:201], v[66:69]
	v_mfma_i32_16x16x64_i8 v[94:97], v[170:173], v[202:205], v[94:97]
	v_mfma_i32_16x16x64_i8 v[94:97], v[174:177], v[206:209], v[94:97]
	v_mfma_i32_16x16x64_i8 v[78:81], v[178:181], v[202:205], v[78:81]
	v_mfma_i32_16x16x64_i8 v[78:81], v[182:185], v[206:209], v[78:81]
	v_mfma_i32_16x16x64_i8 v[90:93], v[170:173], v[210:213], v[90:93]
	v_mfma_i32_16x16x64_i8 v[90:93], v[174:177], v[214:217], v[90:93]
	v_mfma_i32_16x16x64_i8 v[74:77], v[178:181], v[210:213], v[74:77]
	v_mfma_i32_16x16x64_i8 v[74:77], v[182:185], v[214:217], v[74:77]
	s_barrier
	s_add_i32 s4, s81, s63
	v_lshl_add_u64 v[218:219], v[218:219], 0, s[22:23]
	s_mov_b32 m0, s4
	ds_read_b128 v[186:189], v236 offset:49152
	ds_read_b128 v[190:193], v236 offset:50176
	ds_read_b128 v[194:197], v236 offset:51200
	ds_read_b128 v[198:201], v236 offset:52224
	ds_read_b128 v[202:205], v236 offset:53248
	ds_read_b128 v[206:209], v236 offset:54272
	ds_read_b128 v[210:213], v236 offset:55296
	ds_read_b128 v[214:217], v236 offset:56320
	global_load_lds_dwordx4 v[218:219], off
	s_add_i32 m0, s4, 0x2000
	s_add_u32 s4, s18, 0x80080
	v_lshl_add_u64 v[218:219], v[220:221], 0, s[22:23]
	s_addc_u32 s5, s19, 0
	s_add_i32 s18, s82, s63
	global_load_lds_dwordx4 v[218:219], off
	v_lshl_add_u64 v[218:219], s[4:5], 0, v[144:145]
	s_mov_b32 m0, s18
	s_nop 0
	global_load_lds_dwordx4 v[218:219], off
	v_lshl_add_u64 v[218:219], s[4:5], 0, v[148:149]
	s_add_i32 m0, s18, 0x2000
	s_nop 0
	global_load_lds_dwordx4 v[218:219], off
	v_lshl_add_u64 v[218:219], v[222:223], 0, s[22:23]
	s_mov_b32 m0, s77
	s_nop 0
	global_load_lds_dwordx4 v[218:219], off
	v_lshl_add_u64 v[218:219], v[224:225], 0, s[22:23]
	s_mov_b32 m0, s78
	s_nop 0
	global_load_lds_dwordx4 v[218:219], off
	s_waitcnt vmcnt(8)
	s_waitcnt lgkmcnt(0)
	s_barrier
	s_waitcnt lgkmcnt(0)
	v_mfma_i32_16x16x64_i8 v[54:57], v[130:133], v[186:189], v[54:57]
	v_mfma_i32_16x16x64_i8 v[54:57], v[134:137], v[190:193], v[54:57]
	v_mfma_i32_16x16x64_i8 v[18:21], v[162:165], v[186:189], v[18:21]
	v_mfma_i32_16x16x64_i8 v[18:21], v[166:169], v[190:193], v[18:21]
	v_mfma_i32_16x16x64_i8 v[50:53], v[130:133], v[194:197], v[50:53]
	v_mfma_i32_16x16x64_i8 v[50:53], v[134:137], v[198:201], v[50:53]
	v_mfma_i32_16x16x64_i8 v[22:25], v[162:165], v[194:197], v[22:25]
	v_mfma_i32_16x16x64_i8 v[22:25], v[166:169], v[198:201], v[22:25]
	v_mfma_i32_16x16x64_i8 v[62:65], v[130:133], v[202:205], v[62:65]
	v_mfma_i32_16x16x64_i8 v[62:65], v[134:137], v[206:209], v[62:65]
	v_mfma_i32_16x16x64_i8 v[30:33], v[162:165], v[202:205], v[30:33]
	v_mfma_i32_16x16x64_i8 v[30:33], v[166:169], v[206:209], v[30:33]
	v_mfma_i32_16x16x64_i8 v[58:61], v[130:133], v[210:213], v[58:61]
	v_mfma_i32_16x16x64_i8 v[58:61], v[134:137], v[214:217], v[58:61]
	v_mfma_i32_16x16x64_i8 v[26:29], v[162:165], v[210:213], v[26:29]
	v_mfma_i32_16x16x64_i8 v[26:29], v[166:169], v[214:217], v[26:29]
	v_mfma_i32_16x16x64_i8 v[46:49], v[170:173], v[186:189], v[46:49]
	v_mfma_i32_16x16x64_i8 v[46:49], v[174:177], v[190:193], v[46:49]
	v_mfma_i32_16x16x64_i8 v[14:17], v[178:181], v[186:189], v[14:17]
	v_mfma_i32_16x16x64_i8 v[14:17], v[182:185], v[190:193], v[14:17]
	v_mfma_i32_16x16x64_i8 v[42:45], v[170:173], v[194:197], v[42:45]
	v_mfma_i32_16x16x64_i8 v[42:45], v[174:177], v[198:201], v[42:45]
	v_mfma_i32_16x16x64_i8 v[10:13], v[178:181], v[194:197], v[10:13]
	v_mfma_i32_16x16x64_i8 v[10:13], v[182:185], v[198:201], v[10:13]
	v_mfma_i32_16x16x64_i8 v[38:41], v[170:173], v[202:205], v[38:41]
	v_mfma_i32_16x16x64_i8 v[38:41], v[174:177], v[206:209], v[38:41]
	v_mfma_i32_16x16x64_i8 v[6:9], v[178:181], v[202:205], v[6:9]
	v_mfma_i32_16x16x64_i8 v[6:9], v[182:185], v[206:209], v[6:9]
	v_mfma_i32_16x16x64_i8 v[34:37], v[170:173], v[210:213], v[34:37]
	v_mfma_i32_16x16x64_i8 v[34:37], v[174:177], v[214:217], v[34:37]
	v_mfma_i32_16x16x64_i8 v[2:5], v[178:181], v[210:213], v[2:5]
	v_mfma_i32_16x16x64_i8 v[2:5], v[182:185], v[214:217], v[2:5]
	s_barrier
	s_add_i32 s80, s80, 2
	s_add_u32 vcc_hi, vcc_hi, 0x100
	s_addc_u32 s79, s79, 0
	s_cmp_gt_u32 s80, 29
	s_mov_b64 s[4:5], s[6:7]
	s_cbranch_scc0 .LBB0_1367
	s_and_b64 vcc, exec, s[10:11]
	s_cbranch_vccz .LBB0_1370
	s_barrier

.LBB0_1554:
	ds_read_b128 v[114:117], v247
	ds_read_b128 v[118:121], v247 offset:1024
	ds_read_b128 v[126:129], v247 offset:2048
	ds_read_b128 v[134:137], v247 offset:3072
	ds_read_b128 v[138:141], v248
	ds_read_b128 v[142:145], v248 offset:1024
	ds_read_b128 v[154:157], v248 offset:2048
	ds_read_b128 v[158:161], v248 offset:3072
	s_add_u32 s4, s18, 0x100
	s_addc_u32 s5, s19, 0
	s_cmpk_eq_i32 s66, 0xdc
	s_cselect_b32 s29, s23, s5
	s_cselect_b32 s28, s22, s4
	s_cselect_b32 s27, s25, s65
	s_cselect_b32 s26, s24, s64
	v_lshl_add_u64 v[210:211], s[18:19], 0, v[202:203]
	s_add_i32 m0, s17, 0xc000
	ds_read_b128 v[162:165], v249
	ds_read_b128 v[166:169], v249 offset:1024
	ds_read_b128 v[170:173], v249 offset:2048
	ds_read_b128 v[174:177], v249 offset:3072
	ds_read_b128 v[178:181], v249 offset:4096
	ds_read_b128 v[182:185], v249 offset:5120
	ds_read_b128 v[186:189], v249 offset:6144
	ds_read_b128 v[190:193], v249 offset:7168
	global_load_lds_dwordx4 v[210:211], off
	v_lshl_add_u64 v[210:211], s[18:19], 0, v[204:205]
	s_add_i32 m0, s17, 0xe000
	s_nop 0
	global_load_lds_dwordx4 v[210:211], off
	s_waitcnt vmcnt(8)
	s_waitcnt lgkmcnt(0)
	s_barrier
	s_waitcnt lgkmcnt(0)
	v_mfma_f32_16x16x32_bf16 v[150:153], v[114:117], v[162:165], v[150:153]
	v_mfma_f32_16x16x32_bf16 v[150:153], v[118:121], v[166:169], v[150:153]
	v_mfma_f32_16x16x32_bf16 v[146:149], v[126:129], v[162:165], v[146:149]
	v_mfma_f32_16x16x32_bf16 v[146:149], v[134:137], v[166:169], v[146:149]
	v_mfma_f32_16x16x32_bf16 v[110:113], v[114:117], v[170:173], v[110:113]
	v_mfma_f32_16x16x32_bf16 v[110:113], v[118:121], v[174:177], v[110:113]
	v_mfma_f32_16x16x32_bf16 v[106:109], v[126:129], v[170:173], v[106:109]
	v_mfma_f32_16x16x32_bf16 v[106:109], v[134:137], v[174:177], v[106:109]
	v_mfma_f32_16x16x32_bf16 v[94:97], v[114:117], v[178:181], v[94:97]
	v_mfma_f32_16x16x32_bf16 v[94:97], v[118:121], v[182:185], v[94:97]
	v_mfma_f32_16x16x32_bf16 v[90:93], v[126:129], v[178:181], v[90:93]
	v_mfma_f32_16x16x32_bf16 v[90:93], v[134:137], v[182:185], v[90:93]
	v_mfma_f32_16x16x32_bf16 v[78:81], v[114:117], v[186:189], v[78:81]
	v_mfma_f32_16x16x32_bf16 v[78:81], v[118:121], v[190:193], v[78:81]
	v_mfma_f32_16x16x32_bf16 v[74:77], v[126:129], v[186:189], v[74:77]
	v_mfma_f32_16x16x32_bf16 v[74:77], v[134:137], v[190:193], v[74:77]
	v_mfma_f32_16x16x32_bf16 v[130:133], v[138:141], v[162:165], v[130:133]
	v_mfma_f32_16x16x32_bf16 v[130:133], v[142:145], v[166:169], v[130:133]
	v_mfma_f32_16x16x32_bf16 v[122:125], v[154:157], v[162:165], v[122:125]
	v_mfma_f32_16x16x32_bf16 v[122:125], v[158:161], v[166:169], v[122:125]
	v_mfma_f32_16x16x32_bf16 v[102:105], v[138:141], v[170:173], v[102:105]
	v_mfma_f32_16x16x32_bf16 v[102:105], v[142:145], v[174:177], v[102:105]
	v_mfma_f32_16x16x32_bf16 v[98:101], v[154:157], v[170:173], v[98:101]
	v_mfma_f32_16x16x32_bf16 v[98:101], v[158:161], v[174:177], v[98:101]
	v_mfma_f32_16x16x32_bf16 v[86:89], v[138:141], v[178:181], v[86:89]
	v_mfma_f32_16x16x32_bf16 v[86:89], v[142:145], v[182:185], v[86:89]
	v_mfma_f32_16x16x32_bf16 v[82:85], v[154:157], v[178:181], v[82:85]
	v_mfma_f32_16x16x32_bf16 v[82:85], v[158:161], v[182:185], v[82:85]
	v_mfma_f32_16x16x32_bf16 v[70:73], v[138:141], v[186:189], v[70:73]
	v_mfma_f32_16x16x32_bf16 v[70:73], v[142:145], v[190:193], v[70:73]
	v_mfma_f32_16x16x32_bf16 v[66:69], v[154:157], v[186:189], v[66:69]
	v_mfma_f32_16x16x32_bf16 v[66:69], v[158:161], v[190:193], v[66:69]
	s_barrier
	s_add_i32 s18, s42, s16
	v_lshl_add_u64 v[210:211], s[26:27], 0, v[196:197]
	s_mov_b32 m0, s18
	ds_read_b128 v[162:165], v249 offset:16384
	ds_read_b128 v[166:169], v249 offset:17408
	ds_read_b128 v[170:173], v249 offset:18432
	ds_read_b128 v[174:177], v249 offset:19456
	ds_read_b128 v[178:181], v249 offset:20480
	ds_read_b128 v[182:185], v249 offset:21504
	ds_read_b128 v[186:189], v249 offset:22528
	ds_read_b128 v[190:193], v249 offset:23552
	global_load_lds_dwordx4 v[210:211], off
	s_add_i32 m0, s18, 0x2000
	s_add_u32 s18, s26, 0x380000
	v_lshl_add_u64 v[212:213], s[26:27], 0, v[200:201]
	s_addc_u32 s19, s27, 0
	s_add_i32 s67, s43, s16
	global_load_lds_dwordx4 v[212:213], off
	v_lshl_add_u64 v[214:215], s[18:19], 0, v[196:197]
	s_mov_b32 m0, s67
	v_lshl_add_u64 v[216:217], s[28:29], 0, v[198:199]
	global_load_lds_dwordx4 v[214:215], off
	v_lshl_add_u64 v[214:215], s[18:19], 0, v[200:201]
	s_add_i32 m0, s67, 0x2000
	s_nop 0
	global_load_lds_dwordx4 v[214:215], off
	v_lshl_add_u64 v[214:215], s[28:29], 0, v[194:195]
	s_mov_b32 m0, s17
	s_nop 0
	global_load_lds_dwordx4 v[214:215], off
	s_mov_b32 m0, s30
	s_nop 0
	global_load_lds_dwordx4 v[216:217], off
	s_waitcnt vmcnt(8)
	s_waitcnt lgkmcnt(0)
	s_barrier
	s_waitcnt lgkmcnt(0)
	v_mfma_f32_16x16x32_bf16 v[62:65], v[114:117], v[162:165], v[62:65]
	v_mfma_f32_16x16x32_bf16 v[62:65], v[118:121], v[166:169], v[62:65]
	v_mfma_f32_16x16x32_bf16 v[58:61], v[126:129], v[162:165], v[58:61]
	v_mfma_f32_16x16x32_bf16 v[58:61], v[134:137], v[166:169], v[58:61]
	v_mfma_f32_16x16x32_bf16 v[46:49], v[114:117], v[170:173], v[46:49]
	v_mfma_f32_16x16x32_bf16 v[46:49], v[118:121], v[174:177], v[46:49]
	v_mfma_f32_16x16x32_bf16 v[42:45], v[126:129], v[170:173], v[42:45]
	v_mfma_f32_16x16x32_bf16 v[42:45], v[134:137], v[174:177], v[42:45]
	v_mfma_f32_16x16x32_bf16 v[30:33], v[114:117], v[178:181], v[30:33]
	v_mfma_f32_16x16x32_bf16 v[30:33], v[118:121], v[182:185], v[30:33]
	v_mfma_f32_16x16x32_bf16 v[26:29], v[126:129], v[178:181], v[26:29]
	v_mfma_f32_16x16x32_bf16 v[26:29], v[134:137], v[182:185], v[26:29]
	v_mfma_f32_16x16x32_bf16 v[14:17], v[114:117], v[186:189], v[14:17]
	v_mfma_f32_16x16x32_bf16 v[14:17], v[118:121], v[190:193], v[14:17]
	v_mfma_f32_16x16x32_bf16 v[10:13], v[126:129], v[186:189], v[10:13]
	v_mfma_f32_16x16x32_bf16 v[10:13], v[134:137], v[190:193], v[10:13]
	v_mfma_f32_16x16x32_bf16 v[54:57], v[138:141], v[162:165], v[54:57]
	v_mfma_f32_16x16x32_bf16 v[54:57], v[142:145], v[166:169], v[54:57]
	v_mfma_f32_16x16x32_bf16 v[50:53], v[154:157], v[162:165], v[50:53]
	v_mfma_f32_16x16x32_bf16 v[50:53], v[158:161], v[166:169], v[50:53]
	v_mfma_f32_16x16x32_bf16 v[38:41], v[138:141], v[170:173], v[38:41]
	v_mfma_f32_16x16x32_bf16 v[38:41], v[142:145], v[174:177], v[38:41]
	v_mfma_f32_16x16x32_bf16 v[34:37], v[154:157], v[170:173], v[34:37]
	v_mfma_f32_16x16x32_bf16 v[34:37], v[158:161], v[174:177], v[34:37]
	v_mfma_f32_16x16x32_bf16 v[22:25], v[138:141], v[178:181], v[22:25]
	v_mfma_f32_16x16x32_bf16 v[22:25], v[142:145], v[182:185], v[22:25]
	v_mfma_f32_16x16x32_bf16 v[18:21], v[154:157], v[178:181], v[18:21]
	v_mfma_f32_16x16x32_bf16 v[18:21], v[158:161], v[182:185], v[18:21]
	v_mfma_f32_16x16x32_bf16 v[6:9], v[138:141], v[186:189], v[6:9]
	v_mfma_f32_16x16x32_bf16 v[6:9], v[142:145], v[190:193], v[6:9]
	v_mfma_f32_16x16x32_bf16 v[2:5], v[154:157], v[186:189], v[2:5]
	v_mfma_f32_16x16x32_bf16 v[2:5], v[158:161], v[190:193], v[2:5]
	s_barrier
	s_add_i32 s67, 0, 0x18000
	s_add_i32 s68, 0, 0x1c000
	v_add_u32_e32 v134, s67, v244
	v_add_u32_e32 v158, s68, v244
	ds_read_b128 v[114:117], v134
	ds_read_b128 v[118:121], v134 offset:1024
	ds_read_b128 v[126:129], v134 offset:2048
	ds_read_b128 v[134:137], v134 offset:3072
	ds_read_b128 v[138:141], v158
	ds_read_b128 v[142:145], v158 offset:1024
	ds_read_b128 v[154:157], v158 offset:2048
	ds_read_b128 v[158:161], v158 offset:3072
	s_add_u32 s18, s28, 0x380000
	s_addc_u32 s19, s29, 0
	s_mov_b32 m0, s31
	v_lshl_add_u64 v[218:219], s[18:19], 0, v[194:195]
	ds_read_b128 v[162:165], v249 offset:32768
	ds_read_b128 v[166:169], v249 offset:33792
	ds_read_b128 v[170:173], v249 offset:34816
	ds_read_b128 v[174:177], v249 offset:35840
	ds_read_b128 v[178:181], v249 offset:36864
	ds_read_b128 v[182:185], v249 offset:37888
	ds_read_b128 v[186:189], v249 offset:38912
	ds_read_b128 v[190:193], v249 offset:39936
	global_load_lds_dwordx4 v[218:219], off
	v_lshl_add_u64 v[218:219], s[18:19], 0, v[198:199]
	s_mov_b32 m0, s34
	s_nop 0
	global_load_lds_dwordx4 v[218:219], off
	s_waitcnt vmcnt(8)
	s_waitcnt lgkmcnt(0)
	s_barrier
	s_waitcnt lgkmcnt(0)
	v_mfma_f32_16x16x32_bf16 v[150:153], v[114:117], v[162:165], v[150:153]
	v_mfma_f32_16x16x32_bf16 v[150:153], v[118:121], v[166:169], v[150:153]
	v_mfma_f32_16x16x32_bf16 v[146:149], v[126:129], v[162:165], v[146:149]
	v_mfma_f32_16x16x32_bf16 v[146:149], v[134:137], v[166:169], v[146:149]
	v_mfma_f32_16x16x32_bf16 v[110:113], v[114:117], v[170:173], v[110:113]
	v_mfma_f32_16x16x32_bf16 v[110:113], v[118:121], v[174:177], v[110:113]
	v_mfma_f32_16x16x32_bf16 v[106:109], v[126:129], v[170:173], v[106:109]
	v_mfma_f32_16x16x32_bf16 v[106:109], v[134:137], v[174:177], v[106:109]
	v_mfma_f32_16x16x32_bf16 v[94:97], v[114:117], v[178:181], v[94:97]
	v_mfma_f32_16x16x32_bf16 v[94:97], v[118:121], v[182:185], v[94:97]
	v_mfma_f32_16x16x32_bf16 v[90:93], v[126:129], v[178:181], v[90:93]
	v_mfma_f32_16x16x32_bf16 v[90:93], v[134:137], v[182:185], v[90:93]
	v_mfma_f32_16x16x32_bf16 v[78:81], v[114:117], v[186:189], v[78:81]
	v_mfma_f32_16x16x32_bf16 v[78:81], v[118:121], v[190:193], v[78:81]
	v_mfma_f32_16x16x32_bf16 v[74:77], v[126:129], v[186:189], v[74:77]
	v_mfma_f32_16x16x32_bf16 v[74:77], v[134:137], v[190:193], v[74:77]
	v_mfma_f32_16x16x32_bf16 v[130:133], v[138:141], v[162:165], v[130:133]
	v_mfma_f32_16x16x32_bf16 v[130:133], v[142:145], v[166:169], v[130:133]
	v_mfma_f32_16x16x32_bf16 v[122:125], v[154:157], v[162:165], v[122:125]
	v_mfma_f32_16x16x32_bf16 v[122:125], v[158:161], v[166:169], v[122:125]
	v_mfma_f32_16x16x32_bf16 v[102:105], v[138:141], v[170:173], v[102:105]
	v_mfma_f32_16x16x32_bf16 v[102:105], v[142:145], v[174:177], v[102:105]
	v_mfma_f32_16x16x32_bf16 v[98:101], v[154:157], v[170:173], v[98:101]
	v_mfma_f32_16x16x32_bf16 v[98:101], v[158:161], v[174:177], v[98:101]
	v_mfma_f32_16x16x32_bf16 v[86:89], v[138:141], v[178:181], v[86:89]
	v_mfma_f32_16x16x32_bf16 v[86:89], v[142:145], v[182:185], v[86:89]
	v_mfma_f32_16x16x32_bf16 v[82:85], v[154:157], v[178:181], v[82:85]
	v_mfma_f32_16x16x32_bf16 v[82:85], v[158:161], v[182:185], v[82:85]
	v_mfma_f32_16x16x32_bf16 v[70:73], v[138:141], v[186:189], v[70:73]
	v_mfma_f32_16x16x32_bf16 v[70:73], v[142:145], v[190:193], v[70:73]
	v_mfma_f32_16x16x32_bf16 v[66:69], v[154:157], v[186:189], v[66:69]
	v_mfma_f32_16x16x32_bf16 v[66:69], v[158:161], v[190:193], v[66:69]
	s_barrier
	s_add_i32 s18, s67, s16
	v_lshl_add_u64 v[210:211], v[210:211], 0, s[12:13]
	s_mov_b32 m0, s18
	ds_read_b128 v[162:165], v249 offset:49152
	ds_read_b128 v[166:169], v249 offset:50176
	ds_read_b128 v[170:173], v249 offset:51200
	ds_read_b128 v[174:177], v249 offset:52224
	ds_read_b128 v[178:181], v249 offset:53248
	ds_read_b128 v[182:185], v249 offset:54272
	ds_read_b128 v[186:189], v249 offset:55296
	ds_read_b128 v[190:193], v249 offset:56320
	global_load_lds_dwordx4 v[210:211], off
	s_add_i32 m0, s18, 0x2000
	s_add_u32 s18, s26, 0x380080
	v_lshl_add_u64 v[210:211], v[212:213], 0, s[12:13]
	s_addc_u32 s19, s27, 0
	s_add_i32 s26, s68, s16
	global_load_lds_dwordx4 v[210:211], off
	v_lshl_add_u64 v[210:211], s[18:19], 0, v[196:197]
	s_mov_b32 m0, s26
	s_nop 0
	global_load_lds_dwordx4 v[210:211], off
	v_lshl_add_u64 v[210:211], s[18:19], 0, v[200:201]
	s_add_i32 m0, s26, 0x2000
	s_nop 0
	global_load_lds_dwordx4 v[210:211], off
	v_lshl_add_u64 v[210:211], v[214:215], 0, s[12:13]
	s_mov_b32 m0, s38
	s_nop 0
	global_load_lds_dwordx4 v[210:211], off
	v_lshl_add_u64 v[210:211], v[216:217], 0, s[12:13]
	s_mov_b32 m0, s39
	s_nop 0
	global_load_lds_dwordx4 v[210:211], off
	s_waitcnt vmcnt(8)
	s_waitcnt lgkmcnt(0)
	s_barrier
	s_waitcnt lgkmcnt(0)
	v_mfma_f32_16x16x32_bf16 v[62:65], v[114:117], v[162:165], v[62:65]
	v_mfma_f32_16x16x32_bf16 v[62:65], v[118:121], v[166:169], v[62:65]
	v_mfma_f32_16x16x32_bf16 v[58:61], v[126:129], v[162:165], v[58:61]
	v_mfma_f32_16x16x32_bf16 v[58:61], v[134:137], v[166:169], v[58:61]
	v_mfma_f32_16x16x32_bf16 v[46:49], v[114:117], v[170:173], v[46:49]
	v_mfma_f32_16x16x32_bf16 v[46:49], v[118:121], v[174:177], v[46:49]
	v_mfma_f32_16x16x32_bf16 v[42:45], v[126:129], v[170:173], v[42:45]
	v_mfma_f32_16x16x32_bf16 v[42:45], v[134:137], v[174:177], v[42:45]
	v_mfma_f32_16x16x32_bf16 v[30:33], v[114:117], v[178:181], v[30:33]
	v_mfma_f32_16x16x32_bf16 v[30:33], v[118:121], v[182:185], v[30:33]
	v_mfma_f32_16x16x32_bf16 v[26:29], v[126:129], v[178:181], v[26:29]
	v_mfma_f32_16x16x32_bf16 v[26:29], v[134:137], v[182:185], v[26:29]
	v_mfma_f32_16x16x32_bf16 v[14:17], v[114:117], v[186:189], v[14:17]
	v_mfma_f32_16x16x32_bf16 v[14:17], v[118:121], v[190:193], v[14:17]
	v_mfma_f32_16x16x32_bf16 v[10:13], v[126:129], v[186:189], v[10:13]
	v_mfma_f32_16x16x32_bf16 v[10:13], v[134:137], v[190:193], v[10:13]
	v_mfma_f32_16x16x32_bf16 v[54:57], v[138:141], v[162:165], v[54:57]
	v_mfma_f32_16x16x32_bf16 v[54:57], v[142:145], v[166:169], v[54:57]
	v_mfma_f32_16x16x32_bf16 v[50:53], v[154:157], v[162:165], v[50:53]
	v_mfma_f32_16x16x32_bf16 v[50:53], v[158:161], v[166:169], v[50:53]
	v_mfma_f32_16x16x32_bf16 v[38:41], v[138:141], v[170:173], v[38:41]
	v_mfma_f32_16x16x32_bf16 v[38:41], v[142:145], v[174:177], v[38:41]
	v_mfma_f32_16x16x32_bf16 v[34:37], v[154:157], v[170:173], v[34:37]
	v_mfma_f32_16x16x32_bf16 v[34:37], v[158:161], v[174:177], v[34:37]
	v_mfma_f32_16x16x32_bf16 v[22:25], v[138:141], v[178:181], v[22:25]
	v_mfma_f32_16x16x32_bf16 v[22:25], v[142:145], v[182:185], v[22:25]
	v_mfma_f32_16x16x32_bf16 v[18:21], v[154:157], v[178:181], v[18:21]
	v_mfma_f32_16x16x32_bf16 v[18:21], v[158:161], v[182:185], v[18:21]
	v_mfma_f32_16x16x32_bf16 v[6:9], v[138:141], v[186:189], v[6:9]
	v_mfma_f32_16x16x32_bf16 v[6:9], v[142:145], v[190:193], v[6:9]
	v_mfma_f32_16x16x32_bf16 v[2:5], v[154:157], v[186:189], v[2:5]
	v_mfma_f32_16x16x32_bf16 v[2:5], v[158:161], v[190:193], v[2:5]
	s_barrier
	s_add_i32 s66, s66, 2
	s_add_u32 s64, s64, 0x100
	s_addc_u32 s65, s65, 0
	s_cmpk_gt_u32 s66, 0xdd
	s_mov_b64 s[18:19], s[4:5]
	s_cbranch_scc0 .LBB0_1554
	s_and_b64 vcc, exec, s[14:15]
	s_cbranch_vccz .LBB0_1557
	s_barrier

.LBB0_1647:
	ds_read_b128 v[30:33], v200
	ds_read_b128 v[38:41], v200 offset:1024
	ds_read_b128 v[42:45], v200 offset:2048
	ds_read_b128 v[50:53], v200 offset:3072
	ds_read_b128 v[164:167], v201
	ds_read_b128 v[168:171], v201 offset:1024
	ds_read_b128 v[172:175], v201 offset:2048
	ds_read_b128 v[176:179], v201 offset:3072
	s_add_u32 s18, s10, 0xfff00080
	s_addc_u32 s19, s11, -1
	s_cmp_eq_u32 s61, 60
	s_cselect_b32 s69, s0, s19
	s_cselect_b32 s68, s1, s18
	s_cselect_b32 s19, s7, s17
	s_cselect_b32 s18, s9, s16
	v_lshl_add_u64 v[222:223], s[10:11], 0, v[156:157]
	s_add_i32 m0, s39, 0xc000
	ds_read_b128 v[180:183], v202
	ds_read_b128 v[184:187], v202 offset:1024
	ds_read_b128 v[188:191], v202 offset:2048
	ds_read_b128 v[192:195], v202 offset:3072
	ds_read_b128 v[206:209], v202 offset:4096
	ds_read_b128 v[210:213], v202 offset:5120
	ds_read_b128 v[214:217], v202 offset:6144
	ds_read_b128 v[218:221], v202 offset:7168
	global_load_lds_dwordx4 v[222:223], off
	v_lshl_add_u64 v[222:223], s[10:11], 0, v[158:159]
	s_add_i32 m0, s39, 0xe000
	s_nop 0
	global_load_lds_dwordx4 v[222:223], off
	s_waitcnt vmcnt(8)
	s_waitcnt lgkmcnt(0)
	s_barrier
	s_waitcnt lgkmcnt(0)
	v_mfma_f32_16x16x32_bf16 v[138:141], v[30:33], v[180:183], v[138:141]
	v_mfma_f32_16x16x32_bf16 v[138:141], v[38:41], v[184:187], v[138:141]
	v_mfma_f32_16x16x32_bf16 v[142:145], v[42:45], v[180:183], v[142:145]
	v_mfma_f32_16x16x32_bf16 v[142:145], v[50:53], v[184:187], v[142:145]
	v_mfma_f32_16x16x32_bf16 v[122:125], v[30:33], v[188:191], v[122:125]
	v_mfma_f32_16x16x32_bf16 v[122:125], v[38:41], v[192:195], v[122:125]
	v_mfma_f32_16x16x32_bf16 v[126:129], v[42:45], v[188:191], v[126:129]
	v_mfma_f32_16x16x32_bf16 v[126:129], v[50:53], v[192:195], v[126:129]
	v_mfma_f32_16x16x32_bf16 v[106:109], v[30:33], v[206:209], v[106:109]
	v_mfma_f32_16x16x32_bf16 v[106:109], v[38:41], v[210:213], v[106:109]
	v_mfma_f32_16x16x32_bf16 v[110:113], v[42:45], v[206:209], v[110:113]
	v_mfma_f32_16x16x32_bf16 v[110:113], v[50:53], v[210:213], v[110:113]
	v_mfma_f32_16x16x32_bf16 v[90:93], v[30:33], v[214:217], v[90:93]
	v_mfma_f32_16x16x32_bf16 v[90:93], v[38:41], v[218:221], v[90:93]
	v_mfma_f32_16x16x32_bf16 v[94:97], v[42:45], v[214:217], v[94:97]
	v_mfma_f32_16x16x32_bf16 v[94:97], v[50:53], v[218:221], v[94:97]
	v_mfma_f32_16x16x32_bf16 v[130:133], v[164:167], v[180:183], v[130:133]
	v_mfma_f32_16x16x32_bf16 v[130:133], v[168:171], v[184:187], v[130:133]
	v_mfma_f32_16x16x32_bf16 v[134:137], v[172:175], v[180:183], v[134:137]
	v_mfma_f32_16x16x32_bf16 v[134:137], v[176:179], v[184:187], v[134:137]
	v_mfma_f32_16x16x32_bf16 v[114:117], v[164:167], v[188:191], v[114:117]
	v_mfma_f32_16x16x32_bf16 v[114:117], v[168:171], v[192:195], v[114:117]
	v_mfma_f32_16x16x32_bf16 v[118:121], v[172:175], v[188:191], v[118:121]
	v_mfma_f32_16x16x32_bf16 v[118:121], v[176:179], v[192:195], v[118:121]
	v_mfma_f32_16x16x32_bf16 v[98:101], v[164:167], v[206:209], v[98:101]
	v_mfma_f32_16x16x32_bf16 v[98:101], v[168:171], v[210:213], v[98:101]
	v_mfma_f32_16x16x32_bf16 v[102:105], v[172:175], v[206:209], v[102:105]
	v_mfma_f32_16x16x32_bf16 v[102:105], v[176:179], v[210:213], v[102:105]
	v_mfma_f32_16x16x32_bf16 v[82:85], v[164:167], v[214:217], v[82:85]
	v_mfma_f32_16x16x32_bf16 v[82:85], v[168:171], v[218:221], v[82:85]
	v_mfma_f32_16x16x32_bf16 v[86:89], v[172:175], v[214:217], v[86:89]
	v_mfma_f32_16x16x32_bf16 v[86:89], v[176:179], v[218:221], v[86:89]
	s_barrier
	s_add_i32 s63, s77, s37
	v_lshl_add_u64 v[222:223], s[18:19], 0, v[148:149]
	s_mov_b32 m0, s63
	ds_read_b128 v[180:183], v202 offset:16384
	ds_read_b128 v[184:187], v202 offset:17408
	ds_read_b128 v[188:191], v202 offset:18432
	ds_read_b128 v[192:195], v202 offset:19456
	ds_read_b128 v[206:209], v202 offset:20480
	ds_read_b128 v[210:213], v202 offset:21504
	ds_read_b128 v[214:217], v202 offset:22528
	ds_read_b128 v[218:221], v202 offset:23552
	global_load_lds_dwordx4 v[222:223], off
	s_add_i32 m0, s63, 0x2000
	s_add_u32 s82, s18, 0x100000
	v_lshl_add_u64 v[224:225], s[18:19], 0, v[152:153]
	s_addc_u32 s83, s19, 0
	s_add_i32 s63, s78, s37
	global_load_lds_dwordx4 v[224:225], off
	v_lshl_add_u64 v[226:227], s[82:83], 0, v[148:149]
	s_mov_b32 m0, s63
	v_lshl_add_u64 v[228:229], s[68:69], 0, v[150:151]
	global_load_lds_dwordx4 v[226:227], off
	v_lshl_add_u64 v[226:227], s[82:83], 0, v[152:153]
	s_add_i32 m0, s63, 0x2000
	s_nop 0
	global_load_lds_dwordx4 v[226:227], off
	v_lshl_add_u64 v[226:227], s[68:69], 0, v[146:147]
	s_mov_b32 m0, s39
	s_nop 0
	global_load_lds_dwordx4 v[226:227], off
	s_mov_b32 m0, s41
	s_nop 0
	global_load_lds_dwordx4 v[228:229], off
	s_waitcnt vmcnt(8)
	s_waitcnt lgkmcnt(0)
	s_barrier
	s_waitcnt lgkmcnt(0)
	v_mfma_f32_16x16x32_bf16 v[74:77], v[30:33], v[180:183], v[74:77]
	v_mfma_f32_16x16x32_bf16 v[78:81], v[42:45], v[180:183], v[78:81]
	v_mfma_f32_16x16x32_bf16 v[58:61], v[30:33], v[188:191], v[58:61]
	v_mfma_f32_16x16x32_bf16 v[62:65], v[42:45], v[188:191], v[62:65]
	v_mfma_f32_16x16x32_bf16 v[26:29], v[30:33], v[206:209], v[26:29]
	v_mfma_f32_16x16x32_bf16 v[34:37], v[42:45], v[206:209], v[34:37]
	v_mfma_f32_16x16x32_bf16 v[10:13], v[30:33], v[214:217], v[10:13]
	v_mfma_f32_16x16x32_bf16 v[14:17], v[42:45], v[214:217], v[14:17]
	v_mfma_f32_16x16x32_bf16 v[74:77], v[38:41], v[184:187], v[74:77]
	v_mfma_f32_16x16x32_bf16 v[78:81], v[50:53], v[184:187], v[78:81]
	v_mfma_f32_16x16x32_bf16 v[58:61], v[38:41], v[192:195], v[58:61]
	v_mfma_f32_16x16x32_bf16 v[62:65], v[50:53], v[192:195], v[62:65]
	v_mfma_f32_16x16x32_bf16 v[26:29], v[38:41], v[210:213], v[26:29]
	v_mfma_f32_16x16x32_bf16 v[34:37], v[50:53], v[210:213], v[34:37]
	v_mfma_f32_16x16x32_bf16 v[10:13], v[38:41], v[218:221], v[10:13]
	v_mfma_f32_16x16x32_bf16 v[14:17], v[50:53], v[218:221], v[14:17]
	v_mfma_f32_16x16x32_bf16 v[18:21], v[164:167], v[206:209], v[18:21]
	v_mfma_f32_16x16x32_bf16 v[22:25], v[172:175], v[206:209], v[22:25]
	v_mfma_f32_16x16x32_bf16 v[2:5], v[164:167], v[214:217], v[2:5]
	v_mfma_f32_16x16x32_bf16 v[6:9], v[172:175], v[214:217], v[6:9]
	v_mfma_f32_16x16x32_bf16 v[30:33], v[164:167], v[180:183], v[66:69]
	v_mfma_f32_16x16x32_bf16 v[38:41], v[172:175], v[180:183], v[70:73]
	v_mfma_f32_16x16x32_bf16 v[42:45], v[164:167], v[188:191], v[46:49]
	v_mfma_f32_16x16x32_bf16 v[46:49], v[172:175], v[188:191], v[54:57]
	v_mfma_f32_16x16x32_bf16 v[18:21], v[168:171], v[210:213], v[18:21]
	v_mfma_f32_16x16x32_bf16 v[22:25], v[176:179], v[210:213], v[22:25]
	v_mfma_f32_16x16x32_bf16 v[2:5], v[168:171], v[218:221], v[2:5]
	v_mfma_f32_16x16x32_bf16 v[6:9], v[176:179], v[218:221], v[6:9]
	v_mfma_f32_16x16x32_bf16 v[30:33], v[168:171], v[184:187], v[30:33]
	v_mfma_f32_16x16x32_bf16 v[38:41], v[176:179], v[184:187], v[38:41]
	v_mfma_f32_16x16x32_bf16 v[42:45], v[168:171], v[192:195], v[42:45]
	v_mfma_f32_16x16x32_bf16 v[50:53], v[176:179], v[192:195], v[46:49]
	s_barrier
	s_add_i32 s63, 0, 0x18000
	s_add_i32 s82, 0, 0x1c000
	v_add_u32_e32 v70, s63, v196
	v_add_u32_e32 v155, s82, v196
	ds_read_b128 v[46:49], v70
	ds_read_b128 v[54:57], v70 offset:1024
	ds_read_b128 v[66:69], v70 offset:2048
	ds_read_b128 v[70:73], v70 offset:3072
	ds_read_b128 v[164:167], v155
	ds_read_b128 v[168:171], v155 offset:1024
	ds_read_b128 v[172:175], v155 offset:2048
	ds_read_b128 v[176:179], v155 offset:3072
	s_add_u32 s68, s68, 0x100000
	s_addc_u32 s69, s69, 0
	s_mov_b32 m0, s43
	v_lshl_add_u64 v[230:231], s[68:69], 0, v[146:147]
	ds_read_b128 v[180:183], v202 offset:32768
	ds_read_b128 v[184:187], v202 offset:33792
	ds_read_b128 v[188:191], v202 offset:34816
	ds_read_b128 v[192:195], v202 offset:35840
	ds_read_b128 v[206:209], v202 offset:36864
	ds_read_b128 v[210:213], v202 offset:37888
	ds_read_b128 v[214:217], v202 offset:38912
	ds_read_b128 v[218:221], v202 offset:39936
	global_load_lds_dwordx4 v[230:231], off
	v_lshl_add_u64 v[230:231], s[68:69], 0, v[150:151]
	s_mov_b32 m0, s57
	s_nop 0
	global_load_lds_dwordx4 v[230:231], off
	s_waitcnt vmcnt(8)
	s_waitcnt lgkmcnt(0)
	s_barrier
	s_waitcnt lgkmcnt(0)
	v_mfma_f32_16x16x32_bf16 v[138:141], v[46:49], v[180:183], v[138:141]
	v_mfma_f32_16x16x32_bf16 v[138:141], v[54:57], v[184:187], v[138:141]
	v_mfma_f32_16x16x32_bf16 v[142:145], v[66:69], v[180:183], v[142:145]
	v_mfma_f32_16x16x32_bf16 v[142:145], v[70:73], v[184:187], v[142:145]
	v_mfma_f32_16x16x32_bf16 v[122:125], v[46:49], v[188:191], v[122:125]
	v_mfma_f32_16x16x32_bf16 v[122:125], v[54:57], v[192:195], v[122:125]
	v_mfma_f32_16x16x32_bf16 v[126:129], v[66:69], v[188:191], v[126:129]
	v_mfma_f32_16x16x32_bf16 v[126:129], v[70:73], v[192:195], v[126:129]
	v_mfma_f32_16x16x32_bf16 v[106:109], v[46:49], v[206:209], v[106:109]
	v_mfma_f32_16x16x32_bf16 v[106:109], v[54:57], v[210:213], v[106:109]
	v_mfma_f32_16x16x32_bf16 v[110:113], v[66:69], v[206:209], v[110:113]
	v_mfma_f32_16x16x32_bf16 v[110:113], v[70:73], v[210:213], v[110:113]
	v_mfma_f32_16x16x32_bf16 v[90:93], v[46:49], v[214:217], v[90:93]
	v_mfma_f32_16x16x32_bf16 v[90:93], v[54:57], v[218:221], v[90:93]
	v_mfma_f32_16x16x32_bf16 v[94:97], v[66:69], v[214:217], v[94:97]
	v_mfma_f32_16x16x32_bf16 v[94:97], v[70:73], v[218:221], v[94:97]
	v_mfma_f32_16x16x32_bf16 v[130:133], v[164:167], v[180:183], v[130:133]
	v_mfma_f32_16x16x32_bf16 v[130:133], v[168:171], v[184:187], v[130:133]
	v_mfma_f32_16x16x32_bf16 v[134:137], v[172:175], v[180:183], v[134:137]
	v_mfma_f32_16x16x32_bf16 v[134:137], v[176:179], v[184:187], v[134:137]
	v_mfma_f32_16x16x32_bf16 v[114:117], v[164:167], v[188:191], v[114:117]
	v_mfma_f32_16x16x32_bf16 v[114:117], v[168:171], v[192:195], v[114:117]
	v_mfma_f32_16x16x32_bf16 v[118:121], v[172:175], v[188:191], v[118:121]
	v_mfma_f32_16x16x32_bf16 v[118:121], v[176:179], v[192:195], v[118:121]
	v_mfma_f32_16x16x32_bf16 v[98:101], v[164:167], v[206:209], v[98:101]
	v_mfma_f32_16x16x32_bf16 v[98:101], v[168:171], v[210:213], v[98:101]
	v_mfma_f32_16x16x32_bf16 v[102:105], v[172:175], v[206:209], v[102:105]
	v_mfma_f32_16x16x32_bf16 v[102:105], v[176:179], v[210:213], v[102:105]
	v_mfma_f32_16x16x32_bf16 v[82:85], v[164:167], v[214:217], v[82:85]
	v_mfma_f32_16x16x32_bf16 v[82:85], v[168:171], v[218:221], v[82:85]
	v_mfma_f32_16x16x32_bf16 v[86:89], v[172:175], v[214:217], v[86:89]
	v_mfma_f32_16x16x32_bf16 v[86:89], v[176:179], v[218:221], v[86:89]
	s_barrier
	s_add_i32 s63, s63, s37
	v_lshl_add_u64 v[222:223], v[222:223], 0, s[26:27]
	s_mov_b32 m0, s63
	ds_read_b128 v[180:183], v202 offset:49152
	ds_read_b128 v[184:187], v202 offset:50176
	ds_read_b128 v[188:191], v202 offset:51200
	ds_read_b128 v[192:195], v202 offset:52224
	ds_read_b128 v[206:209], v202 offset:53248
	ds_read_b128 v[210:213], v202 offset:54272
	ds_read_b128 v[214:217], v202 offset:55296
	ds_read_b128 v[218:221], v202 offset:56320
	global_load_lds_dwordx4 v[222:223], off
	s_add_i32 m0, s63, 0x2000
	s_add_u32 s18, s18, 0x100080
	v_lshl_add_u64 v[222:223], v[224:225], 0, s[26:27]
	s_addc_u32 s19, s19, 0
	s_add_i32 s63, s82, s37
	global_load_lds_dwordx4 v[222:223], off
	v_lshl_add_u64 v[222:223], s[18:19], 0, v[148:149]
	s_mov_b32 m0, s63
	s_nop 0
	global_load_lds_dwordx4 v[222:223], off
	v_lshl_add_u64 v[222:223], s[18:19], 0, v[152:153]
	s_add_i32 m0, s63, 0x2000
	s_nop 0
	global_load_lds_dwordx4 v[222:223], off
	v_lshl_add_u64 v[222:223], v[226:227], 0, s[26:27]
	s_mov_b32 m0, s71
	s_nop 0
	global_load_lds_dwordx4 v[222:223], off
	v_lshl_add_u64 v[222:223], v[228:229], 0, s[26:27]
	s_mov_b32 m0, s72
	s_nop 0
	global_load_lds_dwordx4 v[222:223], off
	s_waitcnt vmcnt(8)
	s_waitcnt lgkmcnt(0)
	s_barrier
	s_waitcnt lgkmcnt(0)
	v_mfma_f32_16x16x32_bf16 v[74:77], v[46:49], v[180:183], v[74:77]
	v_mfma_f32_16x16x32_bf16 v[78:81], v[66:69], v[180:183], v[78:81]
	v_mfma_f32_16x16x32_bf16 v[58:61], v[46:49], v[188:191], v[58:61]
	v_mfma_f32_16x16x32_bf16 v[62:65], v[66:69], v[188:191], v[62:65]
	v_mfma_f32_16x16x32_bf16 v[26:29], v[46:49], v[206:209], v[26:29]
	v_mfma_f32_16x16x32_bf16 v[34:37], v[66:69], v[206:209], v[34:37]
	v_mfma_f32_16x16x32_bf16 v[10:13], v[46:49], v[214:217], v[10:13]
	v_mfma_f32_16x16x32_bf16 v[14:17], v[66:69], v[214:217], v[14:17]
	v_mfma_f32_16x16x32_bf16 v[74:77], v[54:57], v[184:187], v[74:77]
	v_mfma_f32_16x16x32_bf16 v[78:81], v[70:73], v[184:187], v[78:81]
	v_mfma_f32_16x16x32_bf16 v[58:61], v[54:57], v[192:195], v[58:61]
	v_mfma_f32_16x16x32_bf16 v[62:65], v[70:73], v[192:195], v[62:65]
	v_mfma_f32_16x16x32_bf16 v[26:29], v[54:57], v[210:213], v[26:29]
	v_mfma_f32_16x16x32_bf16 v[34:37], v[70:73], v[210:213], v[34:37]
	v_mfma_f32_16x16x32_bf16 v[10:13], v[54:57], v[218:221], v[10:13]
	v_mfma_f32_16x16x32_bf16 v[14:17], v[70:73], v[218:221], v[14:17]
	v_mfma_f32_16x16x32_bf16 v[30:33], v[164:167], v[180:183], v[30:33]
	v_mfma_f32_16x16x32_bf16 v[66:69], v[168:171], v[184:187], v[30:33]
	v_mfma_f32_16x16x32_bf16 v[30:33], v[172:175], v[180:183], v[38:41]
	v_mfma_f32_16x16x32_bf16 v[70:73], v[176:179], v[184:187], v[30:33]
	v_mfma_f32_16x16x32_bf16 v[30:33], v[164:167], v[188:191], v[42:45]
	v_mfma_f32_16x16x32_bf16 v[46:49], v[168:171], v[192:195], v[30:33]
	v_mfma_f32_16x16x32_bf16 v[30:33], v[172:175], v[188:191], v[50:53]
	v_mfma_f32_16x16x32_bf16 v[18:21], v[164:167], v[206:209], v[18:21]
	v_mfma_f32_16x16x32_bf16 v[22:25], v[172:175], v[206:209], v[22:25]
	v_mfma_f32_16x16x32_bf16 v[2:5], v[164:167], v[214:217], v[2:5]
	v_mfma_f32_16x16x32_bf16 v[6:9], v[172:175], v[214:217], v[6:9]
	v_mfma_f32_16x16x32_bf16 v[54:57], v[176:179], v[192:195], v[30:33]
	v_mfma_f32_16x16x32_bf16 v[18:21], v[168:171], v[210:213], v[18:21]
	v_mfma_f32_16x16x32_bf16 v[22:25], v[176:179], v[210:213], v[22:25]
	v_mfma_f32_16x16x32_bf16 v[2:5], v[168:171], v[218:221], v[2:5]
	v_mfma_f32_16x16x32_bf16 v[6:9], v[176:179], v[218:221], v[6:9]
	s_barrier
	s_add_i32 s61, s61, 2
	s_add_u32 s10, s10, 0x100
	s_addc_u32 s11, s11, 0
	s_add_u32 s16, s16, 0x100
	s_addc_u32 s17, s17, 0
	s_cmp_gt_u32 s61, 61
	s_cbranch_scc0 .LBB0_1647
	s_and_b64 vcc, exec, s[28:29]
	s_cbranch_vccz .LBB0_1650
	s_barrier

.LBB0_1921:
	ds_read_b128 v[130:133], v212
	ds_read_b128 v[134:137], v212 offset:1024
	ds_read_b128 v[138:141], v212 offset:2048
	ds_read_b128 v[142:145], v212 offset:3072
	ds_read_b128 v[146:149], v213
	ds_read_b128 v[150:153], v213 offset:1024
	ds_read_b128 v[154:157], v213 offset:2048
	ds_read_b128 v[158:161], v213 offset:3072
	s_add_u32 s40, s38, 0xfff00080
	s_addc_u32 s41, s39, -1
	s_cmp_eq_u32 s73, 60
	s_cselect_b32 s43, s31, s41
	s_cselect_b32 s42, s69, s40
	s_cselect_b32 s41, s29, s72
	s_cselect_b32 s40, s70, s71
	v_lshl_add_u64 v[216:217], s[38:39], 0, v[178:179]
	s_add_i32 m0, s19, 0xc000
	ds_read_b128 v[162:165], v214
	ds_read_b128 v[166:169], v214 offset:1024
	ds_read_b128 v[186:189], v214 offset:2048
	ds_read_b128 v[190:193], v214 offset:3072
	ds_read_b128 v[194:197], v214 offset:4096
	ds_read_b128 v[198:201], v214 offset:5120
	ds_read_b128 v[202:205], v214 offset:6144
	ds_read_b128 v[206:209], v214 offset:7168
	global_load_lds_dwordx4 v[216:217], off
	v_lshl_add_u64 v[216:217], s[38:39], 0, v[180:181]
	s_add_i32 m0, s19, 0xe000
	s_nop 0
	global_load_lds_dwordx4 v[216:217], off
	s_waitcnt vmcnt(8)
	s_waitcnt lgkmcnt(0)
	s_barrier
	s_waitcnt lgkmcnt(0)
	v_mfma_f32_16x16x32_bf16 v[126:129], v[130:133], v[162:165], v[126:129]
	v_mfma_f32_16x16x32_bf16 v[126:129], v[134:137], v[166:169], v[126:129]
	v_mfma_f32_16x16x32_bf16 v[122:125], v[138:141], v[162:165], v[122:125]
	v_mfma_f32_16x16x32_bf16 v[122:125], v[142:145], v[166:169], v[122:125]
	v_mfma_f32_16x16x32_bf16 v[110:113], v[130:133], v[186:189], v[110:113]
	v_mfma_f32_16x16x32_bf16 v[110:113], v[134:137], v[190:193], v[110:113]
	v_mfma_f32_16x16x32_bf16 v[106:109], v[138:141], v[186:189], v[106:109]
	v_mfma_f32_16x16x32_bf16 v[106:109], v[142:145], v[190:193], v[106:109]
	v_mfma_f32_16x16x32_bf16 v[94:97], v[130:133], v[194:197], v[94:97]
	v_mfma_f32_16x16x32_bf16 v[94:97], v[134:137], v[198:201], v[94:97]
	v_mfma_f32_16x16x32_bf16 v[90:93], v[138:141], v[194:197], v[90:93]
	v_mfma_f32_16x16x32_bf16 v[90:93], v[142:145], v[198:201], v[90:93]
	v_mfma_f32_16x16x32_bf16 v[78:81], v[130:133], v[202:205], v[78:81]
	v_mfma_f32_16x16x32_bf16 v[78:81], v[134:137], v[206:209], v[78:81]
	v_mfma_f32_16x16x32_bf16 v[74:77], v[138:141], v[202:205], v[74:77]
	v_mfma_f32_16x16x32_bf16 v[74:77], v[142:145], v[206:209], v[74:77]
	v_mfma_f32_16x16x32_bf16 v[118:121], v[146:149], v[162:165], v[118:121]
	v_mfma_f32_16x16x32_bf16 v[118:121], v[150:153], v[166:169], v[118:121]
	v_mfma_f32_16x16x32_bf16 v[114:117], v[154:157], v[162:165], v[114:117]
	v_mfma_f32_16x16x32_bf16 v[114:117], v[158:161], v[166:169], v[114:117]
	v_mfma_f32_16x16x32_bf16 v[102:105], v[146:149], v[186:189], v[102:105]
	v_mfma_f32_16x16x32_bf16 v[102:105], v[150:153], v[190:193], v[102:105]
	v_mfma_f32_16x16x32_bf16 v[98:101], v[154:157], v[186:189], v[98:101]
	v_mfma_f32_16x16x32_bf16 v[98:101], v[158:161], v[190:193], v[98:101]
	v_mfma_f32_16x16x32_bf16 v[86:89], v[146:149], v[194:197], v[86:89]
	v_mfma_f32_16x16x32_bf16 v[86:89], v[150:153], v[198:201], v[86:89]
	v_mfma_f32_16x16x32_bf16 v[82:85], v[154:157], v[194:197], v[82:85]
	v_mfma_f32_16x16x32_bf16 v[82:85], v[158:161], v[198:201], v[82:85]
	v_mfma_f32_16x16x32_bf16 v[70:73], v[146:149], v[202:205], v[70:73]
	v_mfma_f32_16x16x32_bf16 v[70:73], v[150:153], v[206:209], v[70:73]
	v_mfma_f32_16x16x32_bf16 v[66:69], v[154:157], v[202:205], v[66:69]
	v_mfma_f32_16x16x32_bf16 v[66:69], v[158:161], v[206:209], v[66:69]
	s_barrier
	s_add_i32 s76, s57, s17
	v_lshl_add_u64 v[216:217], s[40:41], 0, v[172:173]
	s_mov_b32 m0, s76
	ds_read_b128 v[162:165], v214 offset:16384
	ds_read_b128 v[166:169], v214 offset:17408
	ds_read_b128 v[186:189], v214 offset:18432
	ds_read_b128 v[190:193], v214 offset:19456
	ds_read_b128 v[194:197], v214 offset:20480
	ds_read_b128 v[198:201], v214 offset:21504
	ds_read_b128 v[202:205], v214 offset:22528
	ds_read_b128 v[206:209], v214 offset:23552
	global_load_lds_dwordx4 v[216:217], off
	s_add_i32 m0, s76, 0x2000
	s_add_u32 s76, s40, 0x100000
	v_lshl_add_u64 v[218:219], s[40:41], 0, v[176:177]
	s_addc_u32 s77, s41, 0
	s_add_i32 s78, s60, s17
	global_load_lds_dwordx4 v[218:219], off
	v_lshl_add_u64 v[220:221], s[76:77], 0, v[172:173]
	s_mov_b32 m0, s78
	v_lshl_add_u64 v[222:223], s[42:43], 0, v[174:175]
	global_load_lds_dwordx4 v[220:221], off
	v_lshl_add_u64 v[220:221], s[76:77], 0, v[176:177]
	s_add_i32 m0, s78, 0x2000
	s_nop 0
	global_load_lds_dwordx4 v[220:221], off
	v_lshl_add_u64 v[220:221], s[42:43], 0, v[170:171]
	s_mov_b32 m0, s19
	s_nop 0
	global_load_lds_dwordx4 v[220:221], off
	s_mov_b32 m0, s44
	s_nop 0
	global_load_lds_dwordx4 v[222:223], off
	s_waitcnt vmcnt(8)
	s_waitcnt lgkmcnt(0)
	s_barrier
	s_waitcnt lgkmcnt(0)
	v_mfma_f32_16x16x32_bf16 v[62:65], v[130:133], v[162:165], v[62:65]
	v_mfma_f32_16x16x32_bf16 v[62:65], v[134:137], v[166:169], v[62:65]
	v_mfma_f32_16x16x32_bf16 v[58:61], v[138:141], v[162:165], v[58:61]
	v_mfma_f32_16x16x32_bf16 v[58:61], v[142:145], v[166:169], v[58:61]
	v_mfma_f32_16x16x32_bf16 v[46:49], v[130:133], v[186:189], v[46:49]
	v_mfma_f32_16x16x32_bf16 v[46:49], v[134:137], v[190:193], v[46:49]
	v_mfma_f32_16x16x32_bf16 v[42:45], v[138:141], v[186:189], v[42:45]
	v_mfma_f32_16x16x32_bf16 v[42:45], v[142:145], v[190:193], v[42:45]
	v_mfma_f32_16x16x32_bf16 v[30:33], v[130:133], v[194:197], v[30:33]
	v_mfma_f32_16x16x32_bf16 v[30:33], v[134:137], v[198:201], v[30:33]
	v_mfma_f32_16x16x32_bf16 v[26:29], v[138:141], v[194:197], v[26:29]
	v_mfma_f32_16x16x32_bf16 v[26:29], v[142:145], v[198:201], v[26:29]
	v_mfma_f32_16x16x32_bf16 v[14:17], v[130:133], v[202:205], v[14:17]
	v_mfma_f32_16x16x32_bf16 v[14:17], v[134:137], v[206:209], v[14:17]
	v_mfma_f32_16x16x32_bf16 v[10:13], v[138:141], v[202:205], v[10:13]
	v_mfma_f32_16x16x32_bf16 v[10:13], v[142:145], v[206:209], v[10:13]
	v_mfma_f32_16x16x32_bf16 v[54:57], v[146:149], v[162:165], v[54:57]
	v_mfma_f32_16x16x32_bf16 v[54:57], v[150:153], v[166:169], v[54:57]
	v_mfma_f32_16x16x32_bf16 v[50:53], v[154:157], v[162:165], v[50:53]
	v_mfma_f32_16x16x32_bf16 v[50:53], v[158:161], v[166:169], v[50:53]
	v_mfma_f32_16x16x32_bf16 v[38:41], v[146:149], v[186:189], v[38:41]
	v_mfma_f32_16x16x32_bf16 v[38:41], v[150:153], v[190:193], v[38:41]
	v_mfma_f32_16x16x32_bf16 v[34:37], v[154:157], v[186:189], v[34:37]
	v_mfma_f32_16x16x32_bf16 v[34:37], v[158:161], v[190:193], v[34:37]
	v_mfma_f32_16x16x32_bf16 v[22:25], v[146:149], v[194:197], v[22:25]
	v_mfma_f32_16x16x32_bf16 v[22:25], v[150:153], v[198:201], v[22:25]
	v_mfma_f32_16x16x32_bf16 v[18:21], v[154:157], v[194:197], v[18:21]
	v_mfma_f32_16x16x32_bf16 v[18:21], v[158:161], v[198:201], v[18:21]
	v_mfma_f32_16x16x32_bf16 v[6:9], v[146:149], v[202:205], v[6:9]
	v_mfma_f32_16x16x32_bf16 v[6:9], v[150:153], v[206:209], v[6:9]
	v_mfma_f32_16x16x32_bf16 v[2:5], v[154:157], v[202:205], v[2:5]
	v_mfma_f32_16x16x32_bf16 v[2:5], v[158:161], v[206:209], v[2:5]
	s_barrier
	s_add_i32 s76, 0, 0x18000
	s_add_i32 s77, 0, 0x1c000
	v_add_u32_e32 v142, s76, v211
	v_add_u32_e32 v158, s77, v211
	ds_read_b128 v[130:133], v142
	ds_read_b128 v[134:137], v142 offset:1024
	ds_read_b128 v[138:141], v142 offset:2048
	ds_read_b128 v[142:145], v142 offset:3072
	ds_read_b128 v[146:149], v158
	ds_read_b128 v[150:153], v158 offset:1024
	ds_read_b128 v[154:157], v158 offset:2048
	ds_read_b128 v[158:161], v158 offset:3072
	s_add_u32 s42, s42, 0x100000
	s_addc_u32 s43, s43, 0
	s_mov_b32 m0, s45
	v_lshl_add_u64 v[224:225], s[42:43], 0, v[170:171]
	ds_read_b128 v[162:165], v214 offset:32768
	ds_read_b128 v[166:169], v214 offset:33792
	ds_read_b128 v[186:189], v214 offset:34816
	ds_read_b128 v[190:193], v214 offset:35840
	ds_read_b128 v[194:197], v214 offset:36864
	ds_read_b128 v[198:201], v214 offset:37888
	ds_read_b128 v[202:205], v214 offset:38912
	ds_read_b128 v[206:209], v214 offset:39936
	global_load_lds_dwordx4 v[224:225], off
	v_lshl_add_u64 v[224:225], s[42:43], 0, v[174:175]
	s_mov_b32 m0, s46
	s_nop 0
	global_load_lds_dwordx4 v[224:225], off
	s_waitcnt vmcnt(8)
	s_waitcnt lgkmcnt(0)
	s_barrier
	s_waitcnt lgkmcnt(0)
	v_mfma_f32_16x16x32_bf16 v[126:129], v[130:133], v[162:165], v[126:129]
	v_mfma_f32_16x16x32_bf16 v[126:129], v[134:137], v[166:169], v[126:129]
	v_mfma_f32_16x16x32_bf16 v[122:125], v[138:141], v[162:165], v[122:125]
	v_mfma_f32_16x16x32_bf16 v[122:125], v[142:145], v[166:169], v[122:125]
	v_mfma_f32_16x16x32_bf16 v[110:113], v[130:133], v[186:189], v[110:113]
	v_mfma_f32_16x16x32_bf16 v[110:113], v[134:137], v[190:193], v[110:113]
	v_mfma_f32_16x16x32_bf16 v[106:109], v[138:141], v[186:189], v[106:109]
	v_mfma_f32_16x16x32_bf16 v[106:109], v[142:145], v[190:193], v[106:109]
	v_mfma_f32_16x16x32_bf16 v[94:97], v[130:133], v[194:197], v[94:97]
	v_mfma_f32_16x16x32_bf16 v[94:97], v[134:137], v[198:201], v[94:97]
	v_mfma_f32_16x16x32_bf16 v[90:93], v[138:141], v[194:197], v[90:93]
	v_mfma_f32_16x16x32_bf16 v[90:93], v[142:145], v[198:201], v[90:93]
	v_mfma_f32_16x16x32_bf16 v[78:81], v[130:133], v[202:205], v[78:81]
	v_mfma_f32_16x16x32_bf16 v[78:81], v[134:137], v[206:209], v[78:81]
	v_mfma_f32_16x16x32_bf16 v[74:77], v[138:141], v[202:205], v[74:77]
	v_mfma_f32_16x16x32_bf16 v[74:77], v[142:145], v[206:209], v[74:77]
	v_mfma_f32_16x16x32_bf16 v[118:121], v[146:149], v[162:165], v[118:121]
	v_mfma_f32_16x16x32_bf16 v[118:121], v[150:153], v[166:169], v[118:121]
	v_mfma_f32_16x16x32_bf16 v[114:117], v[154:157], v[162:165], v[114:117]
	v_mfma_f32_16x16x32_bf16 v[114:117], v[158:161], v[166:169], v[114:117]
	v_mfma_f32_16x16x32_bf16 v[102:105], v[146:149], v[186:189], v[102:105]
	v_mfma_f32_16x16x32_bf16 v[102:105], v[150:153], v[190:193], v[102:105]
	v_mfma_f32_16x16x32_bf16 v[98:101], v[154:157], v[186:189], v[98:101]
	v_mfma_f32_16x16x32_bf16 v[98:101], v[158:161], v[190:193], v[98:101]
	v_mfma_f32_16x16x32_bf16 v[86:89], v[146:149], v[194:197], v[86:89]
	v_mfma_f32_16x16x32_bf16 v[86:89], v[150:153], v[198:201], v[86:89]
	v_mfma_f32_16x16x32_bf16 v[82:85], v[154:157], v[194:197], v[82:85]
	v_mfma_f32_16x16x32_bf16 v[82:85], v[158:161], v[198:201], v[82:85]
	v_mfma_f32_16x16x32_bf16 v[70:73], v[146:149], v[202:205], v[70:73]
	v_mfma_f32_16x16x32_bf16 v[70:73], v[150:153], v[206:209], v[70:73]
	v_mfma_f32_16x16x32_bf16 v[66:69], v[154:157], v[202:205], v[66:69]
	v_mfma_f32_16x16x32_bf16 v[66:69], v[158:161], v[206:209], v[66:69]
	s_barrier
	s_add_i32 s42, s76, s17
	v_lshl_add_u64 v[216:217], v[216:217], 0, s[8:9]
	s_mov_b32 m0, s42
	ds_read_b128 v[162:165], v214 offset:49152
	ds_read_b128 v[166:169], v214 offset:50176
	ds_read_b128 v[186:189], v214 offset:51200
	ds_read_b128 v[190:193], v214 offset:52224
	ds_read_b128 v[194:197], v214 offset:53248
	ds_read_b128 v[198:201], v214 offset:54272
	ds_read_b128 v[202:205], v214 offset:55296
	ds_read_b128 v[206:209], v214 offset:56320
	global_load_lds_dwordx4 v[216:217], off
	s_add_i32 m0, s42, 0x2000
	s_add_u32 s40, s40, 0x100080
	v_lshl_add_u64 v[216:217], v[218:219], 0, s[8:9]
	s_addc_u32 s41, s41, 0
	s_add_i32 s42, s77, s17
	global_load_lds_dwordx4 v[216:217], off
	v_lshl_add_u64 v[216:217], s[40:41], 0, v[172:173]
	s_mov_b32 m0, s42
	s_nop 0
	global_load_lds_dwordx4 v[216:217], off
	v_lshl_add_u64 v[216:217], s[40:41], 0, v[176:177]
	s_add_i32 m0, s42, 0x2000
	s_nop 0
	global_load_lds_dwordx4 v[216:217], off
	v_lshl_add_u64 v[216:217], v[220:221], 0, s[8:9]
	s_mov_b32 m0, s50
	s_nop 0
	global_load_lds_dwordx4 v[216:217], off
	v_lshl_add_u64 v[216:217], v[222:223], 0, s[8:9]
	s_mov_b32 m0, s51
	s_nop 0
	global_load_lds_dwordx4 v[216:217], off
	s_waitcnt vmcnt(8)
	s_waitcnt lgkmcnt(0)
	s_barrier
	s_waitcnt lgkmcnt(0)
	v_mfma_f32_16x16x32_bf16 v[62:65], v[130:133], v[162:165], v[62:65]
	v_mfma_f32_16x16x32_bf16 v[62:65], v[134:137], v[166:169], v[62:65]
	v_mfma_f32_16x16x32_bf16 v[58:61], v[138:141], v[162:165], v[58:61]
	v_mfma_f32_16x16x32_bf16 v[58:61], v[142:145], v[166:169], v[58:61]
	v_mfma_f32_16x16x32_bf16 v[46:49], v[130:133], v[186:189], v[46:49]
	v_mfma_f32_16x16x32_bf16 v[46:49], v[134:137], v[190:193], v[46:49]
	v_mfma_f32_16x16x32_bf16 v[42:45], v[138:141], v[186:189], v[42:45]
	v_mfma_f32_16x16x32_bf16 v[42:45], v[142:145], v[190:193], v[42:45]
	v_mfma_f32_16x16x32_bf16 v[30:33], v[130:133], v[194:197], v[30:33]
	v_mfma_f32_16x16x32_bf16 v[30:33], v[134:137], v[198:201], v[30:33]
	v_mfma_f32_16x16x32_bf16 v[26:29], v[138:141], v[194:197], v[26:29]
	v_mfma_f32_16x16x32_bf16 v[26:29], v[142:145], v[198:201], v[26:29]
	v_mfma_f32_16x16x32_bf16 v[14:17], v[130:133], v[202:205], v[14:17]
	v_mfma_f32_16x16x32_bf16 v[14:17], v[134:137], v[206:209], v[14:17]
	v_mfma_f32_16x16x32_bf16 v[10:13], v[138:141], v[202:205], v[10:13]
	v_mfma_f32_16x16x32_bf16 v[10:13], v[142:145], v[206:209], v[10:13]
	v_mfma_f32_16x16x32_bf16 v[54:57], v[146:149], v[162:165], v[54:57]
	v_mfma_f32_16x16x32_bf16 v[54:57], v[150:153], v[166:169], v[54:57]
	v_mfma_f32_16x16x32_bf16 v[50:53], v[154:157], v[162:165], v[50:53]
	v_mfma_f32_16x16x32_bf16 v[50:53], v[158:161], v[166:169], v[50:53]
	v_mfma_f32_16x16x32_bf16 v[38:41], v[146:149], v[186:189], v[38:41]
	v_mfma_f32_16x16x32_bf16 v[38:41], v[150:153], v[190:193], v[38:41]
	v_mfma_f32_16x16x32_bf16 v[34:37], v[154:157], v[186:189], v[34:37]
	v_mfma_f32_16x16x32_bf16 v[34:37], v[158:161], v[190:193], v[34:37]
	v_mfma_f32_16x16x32_bf16 v[22:25], v[146:149], v[194:197], v[22:25]
	v_mfma_f32_16x16x32_bf16 v[22:25], v[150:153], v[198:201], v[22:25]
	v_mfma_f32_16x16x32_bf16 v[18:21], v[154:157], v[194:197], v[18:21]
	v_mfma_f32_16x16x32_bf16 v[18:21], v[158:161], v[198:201], v[18:21]
	v_mfma_f32_16x16x32_bf16 v[6:9], v[146:149], v[202:205], v[6:9]
	v_mfma_f32_16x16x32_bf16 v[6:9], v[150:153], v[206:209], v[6:9]
	v_mfma_f32_16x16x32_bf16 v[2:5], v[154:157], v[202:205], v[2:5]
	v_mfma_f32_16x16x32_bf16 v[2:5], v[158:161], v[206:209], v[2:5]
	s_barrier
	s_add_i32 s73, s73, 2
	s_add_u32 s38, s38, 0x100
	s_addc_u32 s39, s39, 0
	s_add_u32 s71, s71, 0x100
	s_addc_u32 s72, s72, 0
	s_cmp_gt_u32 s73, 61
	s_cbranch_scc0 .LBB0_1921
	s_and_b64 vcc, exec, s[10:11]
	s_cbranch_vccz .LBB0_1924
	s_barrier

.LBB0_2056:
	ds_read_b128 v[130:133], v234
	ds_read_b128 v[134:137], v234 offset:1024
	ds_read_b128 v[162:165], v234 offset:2048
	ds_read_b128 v[166:169], v234 offset:3072
	ds_read_b128 v[170:173], v235
	ds_read_b128 v[174:177], v235 offset:1024
	ds_read_b128 v[178:181], v235 offset:2048
	ds_read_b128 v[182:185], v235 offset:3072
	s_add_u32 s4, s2, 0x100
	s_addc_u32 s5, s3, 0
	s_cmp_eq_u32 s93, 28
	s_cselect_b32 s43, s31, s5
	s_cselect_b32 s42, s87, s4
	s_cselect_b32 s19, s29, s92
	s_cselect_b32 s18, s90, s91
	v_lshl_add_u64 v[218:219], s[2:3], 0, v[154:155]
	s_add_i32 m0, s49, 0xc000
	ds_read_b128 v[186:189], v236
	ds_read_b128 v[190:193], v236 offset:1024
	ds_read_b128 v[194:197], v236 offset:2048
	ds_read_b128 v[198:201], v236 offset:3072
	ds_read_b128 v[202:205], v236 offset:4096
	ds_read_b128 v[206:209], v236 offset:5120
	ds_read_b128 v[210:213], v236 offset:6144
	ds_read_b128 v[214:217], v236 offset:7168
	global_load_lds_dwordx4 v[218:219], off
	v_lshl_add_u64 v[218:219], s[2:3], 0, v[156:157]
	s_add_i32 m0, s49, 0xe000
	s_nop 0
	global_load_lds_dwordx4 v[218:219], off
	s_waitcnt vmcnt(8)
	s_waitcnt lgkmcnt(0)
	s_barrier
	s_waitcnt lgkmcnt(0)
	v_mfma_i32_16x16x64_i8 v[118:121], v[130:133], v[186:189], v[118:121]
	v_mfma_i32_16x16x64_i8 v[118:121], v[134:137], v[190:193], v[118:121]
	v_mfma_i32_16x16x64_i8 v[102:105], v[162:165], v[186:189], v[102:105]
	v_mfma_i32_16x16x64_i8 v[102:105], v[166:169], v[190:193], v[102:105]
	v_mfma_i32_16x16x64_i8 v[114:117], v[130:133], v[194:197], v[114:117]
	v_mfma_i32_16x16x64_i8 v[114:117], v[134:137], v[198:201], v[114:117]
	v_mfma_i32_16x16x64_i8 v[98:101], v[162:165], v[194:197], v[98:101]
	v_mfma_i32_16x16x64_i8 v[98:101], v[166:169], v[198:201], v[98:101]
	v_mfma_i32_16x16x64_i8 v[126:129], v[130:133], v[202:205], v[126:129]
	v_mfma_i32_16x16x64_i8 v[126:129], v[134:137], v[206:209], v[126:129]
	v_mfma_i32_16x16x64_i8 v[110:113], v[162:165], v[202:205], v[110:113]
	v_mfma_i32_16x16x64_i8 v[110:113], v[166:169], v[206:209], v[110:113]
	v_mfma_i32_16x16x64_i8 v[122:125], v[130:133], v[210:213], v[122:125]
	v_mfma_i32_16x16x64_i8 v[122:125], v[134:137], v[214:217], v[122:125]
	v_mfma_i32_16x16x64_i8 v[106:109], v[162:165], v[210:213], v[106:109]
	v_mfma_i32_16x16x64_i8 v[106:109], v[166:169], v[214:217], v[106:109]
	v_mfma_i32_16x16x64_i8 v[86:89], v[170:173], v[186:189], v[86:89]
	v_mfma_i32_16x16x64_i8 v[86:89], v[174:177], v[190:193], v[86:89]
	v_mfma_i32_16x16x64_i8 v[70:73], v[178:181], v[186:189], v[70:73]
	v_mfma_i32_16x16x64_i8 v[70:73], v[182:185], v[190:193], v[70:73]
	v_mfma_i32_16x16x64_i8 v[82:85], v[170:173], v[194:197], v[82:85]
	v_mfma_i32_16x16x64_i8 v[82:85], v[174:177], v[198:201], v[82:85]
	v_mfma_i32_16x16x64_i8 v[66:69], v[178:181], v[194:197], v[66:69]
	v_mfma_i32_16x16x64_i8 v[66:69], v[182:185], v[198:201], v[66:69]
	v_mfma_i32_16x16x64_i8 v[94:97], v[170:173], v[202:205], v[94:97]
	v_mfma_i32_16x16x64_i8 v[94:97], v[174:177], v[206:209], v[94:97]
	v_mfma_i32_16x16x64_i8 v[78:81], v[178:181], v[202:205], v[78:81]
	v_mfma_i32_16x16x64_i8 v[78:81], v[182:185], v[206:209], v[78:81]
	v_mfma_i32_16x16x64_i8 v[90:93], v[170:173], v[210:213], v[90:93]
	v_mfma_i32_16x16x64_i8 v[90:93], v[174:177], v[214:217], v[90:93]
	v_mfma_i32_16x16x64_i8 v[74:77], v[178:181], v[210:213], v[74:77]
	v_mfma_i32_16x16x64_i8 v[74:77], v[182:185], v[214:217], v[74:77]
	s_barrier
	s_add_i32 s2, s82, s47
	v_lshl_add_u64 v[218:219], s[18:19], 0, v[144:145]
	s_mov_b32 m0, s2
	ds_read_b128 v[186:189], v236 offset:16384
	ds_read_b128 v[190:193], v236 offset:17408
	ds_read_b128 v[194:197], v236 offset:18432
	ds_read_b128 v[198:201], v236 offset:19456
	ds_read_b128 v[202:205], v236 offset:20480
	ds_read_b128 v[206:209], v236 offset:21504
	ds_read_b128 v[210:213], v236 offset:22528
	ds_read_b128 v[214:217], v236 offset:23552
	global_load_lds_dwordx4 v[218:219], off
	s_add_i32 m0, s2, 0x2000
	s_add_u32 s2, s18, 0x80000
	v_lshl_add_u64 v[220:221], s[18:19], 0, v[148:149]
	s_addc_u32 s3, s19, 0
	s_add_i32 s94, s16, s47
	global_load_lds_dwordx4 v[220:221], off
	v_lshl_add_u64 v[222:223], s[2:3], 0, v[144:145]
	s_mov_b32 m0, s94
	v_lshl_add_u64 v[224:225], s[42:43], 0, v[146:147]
	global_load_lds_dwordx4 v[222:223], off
	v_lshl_add_u64 v[222:223], s[2:3], 0, v[148:149]
	s_add_i32 m0, s94, 0x2000
	s_nop 0
	global_load_lds_dwordx4 v[222:223], off
	v_lshl_add_u64 v[222:223], s[42:43], 0, v[142:143]
	s_mov_b32 m0, s49
	s_nop 0
	global_load_lds_dwordx4 v[222:223], off
	s_mov_b32 m0, s50
	s_nop 0
	global_load_lds_dwordx4 v[224:225], off
	s_waitcnt vmcnt(8)
	s_waitcnt lgkmcnt(0)
	s_barrier
	s_waitcnt lgkmcnt(0)
	v_mfma_i32_16x16x64_i8 v[54:57], v[130:133], v[186:189], v[54:57]
	v_mfma_i32_16x16x64_i8 v[54:57], v[134:137], v[190:193], v[54:57]
	v_mfma_i32_16x16x64_i8 v[18:21], v[162:165], v[186:189], v[18:21]
	v_mfma_i32_16x16x64_i8 v[18:21], v[166:169], v[190:193], v[18:21]
	v_mfma_i32_16x16x64_i8 v[50:53], v[130:133], v[194:197], v[50:53]
	v_mfma_i32_16x16x64_i8 v[50:53], v[134:137], v[198:201], v[50:53]
	v_mfma_i32_16x16x64_i8 v[22:25], v[162:165], v[194:197], v[22:25]
	v_mfma_i32_16x16x64_i8 v[22:25], v[166:169], v[198:201], v[22:25]
	v_mfma_i32_16x16x64_i8 v[62:65], v[130:133], v[202:205], v[62:65]
	v_mfma_i32_16x16x64_i8 v[62:65], v[134:137], v[206:209], v[62:65]
	v_mfma_i32_16x16x64_i8 v[30:33], v[162:165], v[202:205], v[30:33]
	v_mfma_i32_16x16x64_i8 v[30:33], v[166:169], v[206:209], v[30:33]
	v_mfma_i32_16x16x64_i8 v[58:61], v[130:133], v[210:213], v[58:61]
	v_mfma_i32_16x16x64_i8 v[58:61], v[134:137], v[214:217], v[58:61]
	v_mfma_i32_16x16x64_i8 v[26:29], v[162:165], v[210:213], v[26:29]
	v_mfma_i32_16x16x64_i8 v[26:29], v[166:169], v[214:217], v[26:29]
	v_mfma_i32_16x16x64_i8 v[46:49], v[170:173], v[186:189], v[46:49]
	v_mfma_i32_16x16x64_i8 v[46:49], v[174:177], v[190:193], v[46:49]
	v_mfma_i32_16x16x64_i8 v[14:17], v[178:181], v[186:189], v[14:17]
	v_mfma_i32_16x16x64_i8 v[14:17], v[182:185], v[190:193], v[14:17]
	v_mfma_i32_16x16x64_i8 v[42:45], v[170:173], v[194:197], v[42:45]
	v_mfma_i32_16x16x64_i8 v[42:45], v[174:177], v[198:201], v[42:45]
	v_mfma_i32_16x16x64_i8 v[10:13], v[178:181], v[194:197], v[10:13]
	v_mfma_i32_16x16x64_i8 v[10:13], v[182:185], v[198:201], v[10:13]
	v_mfma_i32_16x16x64_i8 v[38:41], v[170:173], v[202:205], v[38:41]
	v_mfma_i32_16x16x64_i8 v[38:41], v[174:177], v[206:209], v[38:41]
	v_mfma_i32_16x16x64_i8 v[6:9], v[178:181], v[202:205], v[6:9]
	v_mfma_i32_16x16x64_i8 v[6:9], v[182:185], v[206:209], v[6:9]
	v_mfma_i32_16x16x64_i8 v[34:37], v[170:173], v[210:213], v[34:37]
	v_mfma_i32_16x16x64_i8 v[34:37], v[174:177], v[214:217], v[34:37]
	v_mfma_i32_16x16x64_i8 v[2:5], v[178:181], v[210:213], v[2:5]
	v_mfma_i32_16x16x64_i8 v[2:5], v[182:185], v[214:217], v[2:5]
	s_barrier
	s_add_i32 s94, 0, 0x18000
	s_add_i32 s95, 0, 0x1c000
	v_add_u32_e32 v166, s94, v232
	v_add_u32_e32 v182, s95, v232
	ds_read_b128 v[130:133], v166
	ds_read_b128 v[134:137], v166 offset:1024
	ds_read_b128 v[162:165], v166 offset:2048
	ds_read_b128 v[166:169], v166 offset:3072
	ds_read_b128 v[170:173], v182
	ds_read_b128 v[174:177], v182 offset:1024
	ds_read_b128 v[178:181], v182 offset:2048
	ds_read_b128 v[182:185], v182 offset:3072
	s_add_u32 s2, s42, 0x80000
	s_addc_u32 s3, s43, 0
	s_mov_b32 m0, s51
	v_lshl_add_u64 v[226:227], s[2:3], 0, v[142:143]
	ds_read_b128 v[186:189], v236 offset:32768
	ds_read_b128 v[190:193], v236 offset:33792
	ds_read_b128 v[194:197], v236 offset:34816
	ds_read_b128 v[198:201], v236 offset:35840
	ds_read_b128 v[202:205], v236 offset:36864
	ds_read_b128 v[206:209], v236 offset:37888
	ds_read_b128 v[210:213], v236 offset:38912
	ds_read_b128 v[214:217], v236 offset:39936
	global_load_lds_dwordx4 v[226:227], off
	v_lshl_add_u64 v[226:227], s[2:3], 0, v[146:147]
	s_mov_b32 m0, s54
	s_nop 0
	global_load_lds_dwordx4 v[226:227], off
	s_waitcnt vmcnt(8)
	s_waitcnt lgkmcnt(0)
	s_barrier
	s_waitcnt lgkmcnt(0)
	v_mfma_i32_16x16x64_i8 v[118:121], v[130:133], v[186:189], v[118:121]
	v_mfma_i32_16x16x64_i8 v[118:121], v[134:137], v[190:193], v[118:121]
	v_mfma_i32_16x16x64_i8 v[102:105], v[162:165], v[186:189], v[102:105]
	v_mfma_i32_16x16x64_i8 v[102:105], v[166:169], v[190:193], v[102:105]
	v_mfma_i32_16x16x64_i8 v[114:117], v[130:133], v[194:197], v[114:117]
	v_mfma_i32_16x16x64_i8 v[114:117], v[134:137], v[198:201], v[114:117]
	v_mfma_i32_16x16x64_i8 v[98:101], v[162:165], v[194:197], v[98:101]
	v_mfma_i32_16x16x64_i8 v[98:101], v[166:169], v[198:201], v[98:101]
	v_mfma_i32_16x16x64_i8 v[126:129], v[130:133], v[202:205], v[126:129]
	v_mfma_i32_16x16x64_i8 v[126:129], v[134:137], v[206:209], v[126:129]
	v_mfma_i32_16x16x64_i8 v[110:113], v[162:165], v[202:205], v[110:113]
	v_mfma_i32_16x16x64_i8 v[110:113], v[166:169], v[206:209], v[110:113]
	v_mfma_i32_16x16x64_i8 v[122:125], v[130:133], v[210:213], v[122:125]
	v_mfma_i32_16x16x64_i8 v[122:125], v[134:137], v[214:217], v[122:125]
	v_mfma_i32_16x16x64_i8 v[106:109], v[162:165], v[210:213], v[106:109]
	v_mfma_i32_16x16x64_i8 v[106:109], v[166:169], v[214:217], v[106:109]
	v_mfma_i32_16x16x64_i8 v[86:89], v[170:173], v[186:189], v[86:89]
	v_mfma_i32_16x16x64_i8 v[86:89], v[174:177], v[190:193], v[86:89]
	v_mfma_i32_16x16x64_i8 v[70:73], v[178:181], v[186:189], v[70:73]
	v_mfma_i32_16x16x64_i8 v[70:73], v[182:185], v[190:193], v[70:73]
	v_mfma_i32_16x16x64_i8 v[82:85], v[170:173], v[194:197], v[82:85]
	v_mfma_i32_16x16x64_i8 v[82:85], v[174:177], v[198:201], v[82:85]
	v_mfma_i32_16x16x64_i8 v[66:69], v[178:181], v[194:197], v[66:69]
	v_mfma_i32_16x16x64_i8 v[66:69], v[182:185], v[198:201], v[66:69]
	v_mfma_i32_16x16x64_i8 v[94:97], v[170:173], v[202:205], v[94:97]
	v_mfma_i32_16x16x64_i8 v[94:97], v[174:177], v[206:209], v[94:97]
	v_mfma_i32_16x16x64_i8 v[78:81], v[178:181], v[202:205], v[78:81]
	v_mfma_i32_16x16x64_i8 v[78:81], v[182:185], v[206:209], v[78:81]
	v_mfma_i32_16x16x64_i8 v[90:93], v[170:173], v[210:213], v[90:93]
	v_mfma_i32_16x16x64_i8 v[90:93], v[174:177], v[214:217], v[90:93]
	v_mfma_i32_16x16x64_i8 v[74:77], v[178:181], v[210:213], v[74:77]
	v_mfma_i32_16x16x64_i8 v[74:77], v[182:185], v[214:217], v[74:77]
	s_barrier
	s_add_i32 s2, s94, s47
	v_lshl_add_u64 v[218:219], v[218:219], 0, s[14:15]
	s_mov_b32 m0, s2
	ds_read_b128 v[186:189], v236 offset:49152
	ds_read_b128 v[190:193], v236 offset:50176
	ds_read_b128 v[194:197], v236 offset:51200
	ds_read_b128 v[198:201], v236 offset:52224
	ds_read_b128 v[202:205], v236 offset:53248
	ds_read_b128 v[206:209], v236 offset:54272
	ds_read_b128 v[210:213], v236 offset:55296
	ds_read_b128 v[214:217], v236 offset:56320
	global_load_lds_dwordx4 v[218:219], off
	s_add_i32 m0, s2, 0x2000
	s_add_u32 s2, s18, 0x80080
	v_lshl_add_u64 v[218:219], v[220:221], 0, s[14:15]
	s_addc_u32 s3, s19, 0
	s_add_i32 s18, s95, s47
	global_load_lds_dwordx4 v[218:219], off
	v_lshl_add_u64 v[218:219], s[2:3], 0, v[144:145]
	s_mov_b32 m0, s18
	s_nop 0
	global_load_lds_dwordx4 v[218:219], off
	v_lshl_add_u64 v[218:219], s[2:3], 0, v[148:149]
	s_add_i32 m0, s18, 0x2000
	s_nop 0
	global_load_lds_dwordx4 v[218:219], off
	v_lshl_add_u64 v[218:219], v[222:223], 0, s[14:15]
	s_mov_b32 m0, s63
	s_nop 0
	global_load_lds_dwordx4 v[218:219], off
	v_lshl_add_u64 v[218:219], v[224:225], 0, s[14:15]
	s_mov_b32 m0, s64
	s_nop 0
	global_load_lds_dwordx4 v[218:219], off
	s_waitcnt vmcnt(8)
	s_waitcnt lgkmcnt(0)
	s_barrier
	s_waitcnt lgkmcnt(0)
	v_mfma_i32_16x16x64_i8 v[54:57], v[130:133], v[186:189], v[54:57]
	v_mfma_i32_16x16x64_i8 v[54:57], v[134:137], v[190:193], v[54:57]
	v_mfma_i32_16x16x64_i8 v[18:21], v[162:165], v[186:189], v[18:21]
	v_mfma_i32_16x16x64_i8 v[18:21], v[166:169], v[190:193], v[18:21]
	v_mfma_i32_16x16x64_i8 v[50:53], v[130:133], v[194:197], v[50:53]
	v_mfma_i32_16x16x64_i8 v[50:53], v[134:137], v[198:201], v[50:53]
	v_mfma_i32_16x16x64_i8 v[22:25], v[162:165], v[194:197], v[22:25]
	v_mfma_i32_16x16x64_i8 v[22:25], v[166:169], v[198:201], v[22:25]
	v_mfma_i32_16x16x64_i8 v[62:65], v[130:133], v[202:205], v[62:65]
	v_mfma_i32_16x16x64_i8 v[62:65], v[134:137], v[206:209], v[62:65]
	v_mfma_i32_16x16x64_i8 v[30:33], v[162:165], v[202:205], v[30:33]
	v_mfma_i32_16x16x64_i8 v[30:33], v[166:169], v[206:209], v[30:33]
	v_mfma_i32_16x16x64_i8 v[58:61], v[130:133], v[210:213], v[58:61]
	v_mfma_i32_16x16x64_i8 v[58:61], v[134:137], v[214:217], v[58:61]
	v_mfma_i32_16x16x64_i8 v[26:29], v[162:165], v[210:213], v[26:29]
	v_mfma_i32_16x16x64_i8 v[26:29], v[166:169], v[214:217], v[26:29]
	v_mfma_i32_16x16x64_i8 v[46:49], v[170:173], v[186:189], v[46:49]
	v_mfma_i32_16x16x64_i8 v[46:49], v[174:177], v[190:193], v[46:49]
	v_mfma_i32_16x16x64_i8 v[14:17], v[178:181], v[186:189], v[14:17]
	v_mfma_i32_16x16x64_i8 v[14:17], v[182:185], v[190:193], v[14:17]
	v_mfma_i32_16x16x64_i8 v[42:45], v[170:173], v[194:197], v[42:45]
	v_mfma_i32_16x16x64_i8 v[42:45], v[174:177], v[198:201], v[42:45]
	v_mfma_i32_16x16x64_i8 v[10:13], v[178:181], v[194:197], v[10:13]
	v_mfma_i32_16x16x64_i8 v[10:13], v[182:185], v[198:201], v[10:13]
	v_mfma_i32_16x16x64_i8 v[38:41], v[170:173], v[202:205], v[38:41]
	v_mfma_i32_16x16x64_i8 v[38:41], v[174:177], v[206:209], v[38:41]
	v_mfma_i32_16x16x64_i8 v[6:9], v[178:181], v[202:205], v[6:9]
	v_mfma_i32_16x16x64_i8 v[6:9], v[182:185], v[206:209], v[6:9]
	v_mfma_i32_16x16x64_i8 v[34:37], v[170:173], v[210:213], v[34:37]
	v_mfma_i32_16x16x64_i8 v[34:37], v[174:177], v[214:217], v[34:37]
	v_mfma_i32_16x16x64_i8 v[2:5], v[178:181], v[210:213], v[2:5]
	v_mfma_i32_16x16x64_i8 v[2:5], v[182:185], v[214:217], v[2:5]
	s_barrier
	s_add_i32 s93, s93, 2
	s_add_u32 s91, s91, 0x100
	s_addc_u32 s92, s92, 0
	s_cmp_gt_u32 s93, 29
	s_mov_b64 s[2:3], s[4:5]
	s_cbranch_scc0 .LBB0_2056
	s_and_b64 vcc, exec, s[8:9]
	s_cbranch_vccz .LBB0_2059
	s_barrier

.LBB0_2241:
	ds_read_b128 v[130:133], v212
	ds_read_b128 v[134:137], v212 offset:1024
	ds_read_b128 v[138:141], v212 offset:2048
	ds_read_b128 v[142:145], v212 offset:3072
	ds_read_b128 v[146:149], v213
	ds_read_b128 v[150:153], v213 offset:1024
	ds_read_b128 v[154:157], v213 offset:2048
	ds_read_b128 v[158:161], v213 offset:3072
	s_add_u32 s36, s18, 0x100
	s_addc_u32 s37, s19, 0
	s_cmpk_eq_i32 s71, 0xdc
	s_cselect_b32 s41, s3, s37
	s_cselect_b32 s40, s2, s36
	s_cselect_b32 s39, s35, s70
	s_cselect_b32 s38, s34, s69
	v_lshl_add_u64 v[216:217], s[18:19], 0, v[178:179]
	s_add_i32 m0, s44, 0xc000
	ds_read_b128 v[162:165], v214
	ds_read_b128 v[166:169], v214 offset:1024
	ds_read_b128 v[186:189], v214 offset:2048
	ds_read_b128 v[190:193], v214 offset:3072
	ds_read_b128 v[194:197], v214 offset:4096
	ds_read_b128 v[198:201], v214 offset:5120
	ds_read_b128 v[202:205], v214 offset:6144
	ds_read_b128 v[206:209], v214 offset:7168
	global_load_lds_dwordx4 v[216:217], off
	v_lshl_add_u64 v[216:217], s[18:19], 0, v[180:181]
	s_add_i32 m0, s44, 0xe000
	s_nop 0
	global_load_lds_dwordx4 v[216:217], off
	s_waitcnt vmcnt(8)
	s_waitcnt lgkmcnt(0)
	s_barrier
	s_waitcnt lgkmcnt(0)
	v_mfma_f32_16x16x32_bf16 v[126:129], v[130:133], v[162:165], v[126:129]
	v_mfma_f32_16x16x32_bf16 v[126:129], v[134:137], v[166:169], v[126:129]
	v_mfma_f32_16x16x32_bf16 v[122:125], v[138:141], v[162:165], v[122:125]
	v_mfma_f32_16x16x32_bf16 v[122:125], v[142:145], v[166:169], v[122:125]
	v_mfma_f32_16x16x32_bf16 v[110:113], v[130:133], v[186:189], v[110:113]
	v_mfma_f32_16x16x32_bf16 v[110:113], v[134:137], v[190:193], v[110:113]
	v_mfma_f32_16x16x32_bf16 v[106:109], v[138:141], v[186:189], v[106:109]
	v_mfma_f32_16x16x32_bf16 v[106:109], v[142:145], v[190:193], v[106:109]
	v_mfma_f32_16x16x32_bf16 v[94:97], v[130:133], v[194:197], v[94:97]
	v_mfma_f32_16x16x32_bf16 v[94:97], v[134:137], v[198:201], v[94:97]
	v_mfma_f32_16x16x32_bf16 v[90:93], v[138:141], v[194:197], v[90:93]
	v_mfma_f32_16x16x32_bf16 v[90:93], v[142:145], v[198:201], v[90:93]
	v_mfma_f32_16x16x32_bf16 v[78:81], v[130:133], v[202:205], v[78:81]
	v_mfma_f32_16x16x32_bf16 v[78:81], v[134:137], v[206:209], v[78:81]
	v_mfma_f32_16x16x32_bf16 v[74:77], v[138:141], v[202:205], v[74:77]
	v_mfma_f32_16x16x32_bf16 v[74:77], v[142:145], v[206:209], v[74:77]
	v_mfma_f32_16x16x32_bf16 v[118:121], v[146:149], v[162:165], v[118:121]
	v_mfma_f32_16x16x32_bf16 v[118:121], v[150:153], v[166:169], v[118:121]
	v_mfma_f32_16x16x32_bf16 v[114:117], v[154:157], v[162:165], v[114:117]
	v_mfma_f32_16x16x32_bf16 v[114:117], v[158:161], v[166:169], v[114:117]
	v_mfma_f32_16x16x32_bf16 v[102:105], v[146:149], v[186:189], v[102:105]
	v_mfma_f32_16x16x32_bf16 v[102:105], v[150:153], v[190:193], v[102:105]
	v_mfma_f32_16x16x32_bf16 v[98:101], v[154:157], v[186:189], v[98:101]
	v_mfma_f32_16x16x32_bf16 v[98:101], v[158:161], v[190:193], v[98:101]
	v_mfma_f32_16x16x32_bf16 v[86:89], v[146:149], v[194:197], v[86:89]
	v_mfma_f32_16x16x32_bf16 v[86:89], v[150:153], v[198:201], v[86:89]
	v_mfma_f32_16x16x32_bf16 v[82:85], v[154:157], v[194:197], v[82:85]
	v_mfma_f32_16x16x32_bf16 v[82:85], v[158:161], v[198:201], v[82:85]
	v_mfma_f32_16x16x32_bf16 v[70:73], v[146:149], v[202:205], v[70:73]
	v_mfma_f32_16x16x32_bf16 v[70:73], v[150:153], v[206:209], v[70:73]
	v_mfma_f32_16x16x32_bf16 v[66:69], v[154:157], v[202:205], v[66:69]
	v_mfma_f32_16x16x32_bf16 v[66:69], v[158:161], v[206:209], v[66:69]
	s_barrier
	s_add_i32 s18, s56, s43
	v_lshl_add_u64 v[216:217], s[38:39], 0, v[172:173]
	s_mov_b32 m0, s18
	ds_read_b128 v[162:165], v214 offset:16384
	ds_read_b128 v[166:169], v214 offset:17408
	ds_read_b128 v[186:189], v214 offset:18432
	ds_read_b128 v[190:193], v214 offset:19456
	ds_read_b128 v[194:197], v214 offset:20480
	ds_read_b128 v[198:201], v214 offset:21504
	ds_read_b128 v[202:205], v214 offset:22528
	ds_read_b128 v[206:209], v214 offset:23552
	global_load_lds_dwordx4 v[216:217], off
	s_add_i32 m0, s18, 0x2000
	s_add_u32 s18, s38, 0x380000
	v_lshl_add_u64 v[218:219], s[38:39], 0, v[176:177]
	s_addc_u32 s19, s39, 0
	s_add_i32 s72, s57, s43
	global_load_lds_dwordx4 v[218:219], off
	v_lshl_add_u64 v[220:221], s[18:19], 0, v[172:173]
	s_mov_b32 m0, s72
	v_lshl_add_u64 v[222:223], s[40:41], 0, v[174:175]
	global_load_lds_dwordx4 v[220:221], off
	v_lshl_add_u64 v[220:221], s[18:19], 0, v[176:177]
	s_add_i32 m0, s72, 0x2000
	s_nop 0
	global_load_lds_dwordx4 v[220:221], off
	v_lshl_add_u64 v[220:221], s[40:41], 0, v[170:171]
	s_mov_b32 m0, s44
	s_nop 0
	global_load_lds_dwordx4 v[220:221], off
	s_mov_b32 m0, s45
	s_nop 0
	global_load_lds_dwordx4 v[222:223], off
	s_waitcnt vmcnt(8)
	s_waitcnt lgkmcnt(0)
	s_barrier
	s_waitcnt lgkmcnt(0)
	v_mfma_f32_16x16x32_bf16 v[62:65], v[130:133], v[162:165], v[62:65]
	v_mfma_f32_16x16x32_bf16 v[62:65], v[134:137], v[166:169], v[62:65]
	v_mfma_f32_16x16x32_bf16 v[58:61], v[138:141], v[162:165], v[58:61]
	v_mfma_f32_16x16x32_bf16 v[58:61], v[142:145], v[166:169], v[58:61]
	v_mfma_f32_16x16x32_bf16 v[46:49], v[130:133], v[186:189], v[46:49]
	v_mfma_f32_16x16x32_bf16 v[46:49], v[134:137], v[190:193], v[46:49]
	v_mfma_f32_16x16x32_bf16 v[42:45], v[138:141], v[186:189], v[42:45]
	v_mfma_f32_16x16x32_bf16 v[42:45], v[142:145], v[190:193], v[42:45]
	v_mfma_f32_16x16x32_bf16 v[30:33], v[130:133], v[194:197], v[30:33]
	v_mfma_f32_16x16x32_bf16 v[30:33], v[134:137], v[198:201], v[30:33]
	v_mfma_f32_16x16x32_bf16 v[26:29], v[138:141], v[194:197], v[26:29]
	v_mfma_f32_16x16x32_bf16 v[26:29], v[142:145], v[198:201], v[26:29]
	v_mfma_f32_16x16x32_bf16 v[14:17], v[130:133], v[202:205], v[14:17]
	v_mfma_f32_16x16x32_bf16 v[14:17], v[134:137], v[206:209], v[14:17]
	v_mfma_f32_16x16x32_bf16 v[10:13], v[138:141], v[202:205], v[10:13]
	v_mfma_f32_16x16x32_bf16 v[10:13], v[142:145], v[206:209], v[10:13]
	v_mfma_f32_16x16x32_bf16 v[54:57], v[146:149], v[162:165], v[54:57]
	v_mfma_f32_16x16x32_bf16 v[54:57], v[150:153], v[166:169], v[54:57]
	v_mfma_f32_16x16x32_bf16 v[50:53], v[154:157], v[162:165], v[50:53]
	v_mfma_f32_16x16x32_bf16 v[50:53], v[158:161], v[166:169], v[50:53]
	v_mfma_f32_16x16x32_bf16 v[38:41], v[146:149], v[186:189], v[38:41]
	v_mfma_f32_16x16x32_bf16 v[38:41], v[150:153], v[190:193], v[38:41]
	v_mfma_f32_16x16x32_bf16 v[34:37], v[154:157], v[186:189], v[34:37]
	v_mfma_f32_16x16x32_bf16 v[34:37], v[158:161], v[190:193], v[34:37]
	v_mfma_f32_16x16x32_bf16 v[22:25], v[146:149], v[194:197], v[22:25]
	v_mfma_f32_16x16x32_bf16 v[22:25], v[150:153], v[198:201], v[22:25]
	v_mfma_f32_16x16x32_bf16 v[18:21], v[154:157], v[194:197], v[18:21]
	v_mfma_f32_16x16x32_bf16 v[18:21], v[158:161], v[198:201], v[18:21]
	v_mfma_f32_16x16x32_bf16 v[6:9], v[146:149], v[202:205], v[6:9]
	v_mfma_f32_16x16x32_bf16 v[6:9], v[150:153], v[206:209], v[6:9]
	v_mfma_f32_16x16x32_bf16 v[2:5], v[154:157], v[202:205], v[2:5]
	v_mfma_f32_16x16x32_bf16 v[2:5], v[158:161], v[206:209], v[2:5]
	s_barrier
	s_add_i32 s72, 0, 0x18000
	s_add_i32 s73, 0, 0x1c000
	v_add_u32_e32 v142, s72, v211
	v_add_u32_e32 v158, s73, v211
	ds_read_b128 v[130:133], v142
	ds_read_b128 v[134:137], v142 offset:1024
	ds_read_b128 v[138:141], v142 offset:2048
	ds_read_b128 v[142:145], v142 offset:3072
	ds_read_b128 v[146:149], v158
	ds_read_b128 v[150:153], v158 offset:1024
	ds_read_b128 v[154:157], v158 offset:2048
	ds_read_b128 v[158:161], v158 offset:3072
	s_add_u32 s18, s40, 0x380000
	s_addc_u32 s19, s41, 0
	s_mov_b32 m0, s46
	v_lshl_add_u64 v[224:225], s[18:19], 0, v[170:171]
	ds_read_b128 v[162:165], v214 offset:32768
	ds_read_b128 v[166:169], v214 offset:33792
	ds_read_b128 v[186:189], v214 offset:34816
	ds_read_b128 v[190:193], v214 offset:35840
	ds_read_b128 v[194:197], v214 offset:36864
	ds_read_b128 v[198:201], v214 offset:37888
	ds_read_b128 v[202:205], v214 offset:38912
	ds_read_b128 v[206:209], v214 offset:39936
	global_load_lds_dwordx4 v[224:225], off
	v_lshl_add_u64 v[224:225], s[18:19], 0, v[174:175]
	s_mov_b32 m0, s47
	s_nop 0
	global_load_lds_dwordx4 v[224:225], off
	s_waitcnt vmcnt(8)
	s_waitcnt lgkmcnt(0)
	s_barrier
	s_waitcnt lgkmcnt(0)
	v_mfma_f32_16x16x32_bf16 v[126:129], v[130:133], v[162:165], v[126:129]
	v_mfma_f32_16x16x32_bf16 v[126:129], v[134:137], v[166:169], v[126:129]
	v_mfma_f32_16x16x32_bf16 v[122:125], v[138:141], v[162:165], v[122:125]
	v_mfma_f32_16x16x32_bf16 v[122:125], v[142:145], v[166:169], v[122:125]
	v_mfma_f32_16x16x32_bf16 v[110:113], v[130:133], v[186:189], v[110:113]
	v_mfma_f32_16x16x32_bf16 v[110:113], v[134:137], v[190:193], v[110:113]
	v_mfma_f32_16x16x32_bf16 v[106:109], v[138:141], v[186:189], v[106:109]
	v_mfma_f32_16x16x32_bf16 v[106:109], v[142:145], v[190:193], v[106:109]
	v_mfma_f32_16x16x32_bf16 v[94:97], v[130:133], v[194:197], v[94:97]
	v_mfma_f32_16x16x32_bf16 v[94:97], v[134:137], v[198:201], v[94:97]
	v_mfma_f32_16x16x32_bf16 v[90:93], v[138:141], v[194:197], v[90:93]
	v_mfma_f32_16x16x32_bf16 v[90:93], v[142:145], v[198:201], v[90:93]
	v_mfma_f32_16x16x32_bf16 v[78:81], v[130:133], v[202:205], v[78:81]
	v_mfma_f32_16x16x32_bf16 v[78:81], v[134:137], v[206:209], v[78:81]
	v_mfma_f32_16x16x32_bf16 v[74:77], v[138:141], v[202:205], v[74:77]
	v_mfma_f32_16x16x32_bf16 v[74:77], v[142:145], v[206:209], v[74:77]
	v_mfma_f32_16x16x32_bf16 v[118:121], v[146:149], v[162:165], v[118:121]
	v_mfma_f32_16x16x32_bf16 v[118:121], v[150:153], v[166:169], v[118:121]
	v_mfma_f32_16x16x32_bf16 v[114:117], v[154:157], v[162:165], v[114:117]
	v_mfma_f32_16x16x32_bf16 v[114:117], v[158:161], v[166:169], v[114:117]
	v_mfma_f32_16x16x32_bf16 v[102:105], v[146:149], v[186:189], v[102:105]
	v_mfma_f32_16x16x32_bf16 v[102:105], v[150:153], v[190:193], v[102:105]
	v_mfma_f32_16x16x32_bf16 v[98:101], v[154:157], v[186:189], v[98:101]
	v_mfma_f32_16x16x32_bf16 v[98:101], v[158:161], v[190:193], v[98:101]
	v_mfma_f32_16x16x32_bf16 v[86:89], v[146:149], v[194:197], v[86:89]
	v_mfma_f32_16x16x32_bf16 v[86:89], v[150:153], v[198:201], v[86:89]
	v_mfma_f32_16x16x32_bf16 v[82:85], v[154:157], v[194:197], v[82:85]
	v_mfma_f32_16x16x32_bf16 v[82:85], v[158:161], v[198:201], v[82:85]
	v_mfma_f32_16x16x32_bf16 v[70:73], v[146:149], v[202:205], v[70:73]
	v_mfma_f32_16x16x32_bf16 v[70:73], v[150:153], v[206:209], v[70:73]
	v_mfma_f32_16x16x32_bf16 v[66:69], v[154:157], v[202:205], v[66:69]
	v_mfma_f32_16x16x32_bf16 v[66:69], v[158:161], v[206:209], v[66:69]
	s_barrier
	s_add_i32 s18, s72, s43
	v_lshl_add_u64 v[216:217], v[216:217], 0, s[8:9]
	s_mov_b32 m0, s18
	ds_read_b128 v[162:165], v214 offset:49152
	ds_read_b128 v[166:169], v214 offset:50176
	ds_read_b128 v[186:189], v214 offset:51200
	ds_read_b128 v[190:193], v214 offset:52224
	ds_read_b128 v[194:197], v214 offset:53248
	ds_read_b128 v[198:201], v214 offset:54272
	ds_read_b128 v[202:205], v214 offset:55296
	ds_read_b128 v[206:209], v214 offset:56320
	global_load_lds_dwordx4 v[216:217], off
	s_add_i32 m0, s18, 0x2000
	s_add_u32 s18, s38, 0x380080
	v_lshl_add_u64 v[216:217], v[218:219], 0, s[8:9]
	s_addc_u32 s19, s39, 0
	s_add_i32 s38, s73, s43
	global_load_lds_dwordx4 v[216:217], off
	v_lshl_add_u64 v[216:217], s[18:19], 0, v[172:173]
	s_mov_b32 m0, s38
	s_nop 0
	global_load_lds_dwordx4 v[216:217], off
	v_lshl_add_u64 v[216:217], s[18:19], 0, v[176:177]
	s_add_i32 m0, s38, 0x2000
	s_nop 0
	global_load_lds_dwordx4 v[216:217], off
	v_lshl_add_u64 v[216:217], v[220:221], 0, s[8:9]
	s_mov_b32 m0, s51
	s_nop 0
	global_load_lds_dwordx4 v[216:217], off
	v_lshl_add_u64 v[216:217], v[222:223], 0, s[8:9]
	s_mov_b32 m0, s54
	s_nop 0
	global_load_lds_dwordx4 v[216:217], off
	s_waitcnt vmcnt(8)
	s_waitcnt lgkmcnt(0)
	s_barrier
	s_waitcnt lgkmcnt(0)
	v_mfma_f32_16x16x32_bf16 v[62:65], v[130:133], v[162:165], v[62:65]
	v_mfma_f32_16x16x32_bf16 v[62:65], v[134:137], v[166:169], v[62:65]
	v_mfma_f32_16x16x32_bf16 v[58:61], v[138:141], v[162:165], v[58:61]
	v_mfma_f32_16x16x32_bf16 v[58:61], v[142:145], v[166:169], v[58:61]
	v_mfma_f32_16x16x32_bf16 v[46:49], v[130:133], v[186:189], v[46:49]
	v_mfma_f32_16x16x32_bf16 v[46:49], v[134:137], v[190:193], v[46:49]
	v_mfma_f32_16x16x32_bf16 v[42:45], v[138:141], v[186:189], v[42:45]
	v_mfma_f32_16x16x32_bf16 v[42:45], v[142:145], v[190:193], v[42:45]
	v_mfma_f32_16x16x32_bf16 v[30:33], v[130:133], v[194:197], v[30:33]
	v_mfma_f32_16x16x32_bf16 v[30:33], v[134:137], v[198:201], v[30:33]
	v_mfma_f32_16x16x32_bf16 v[26:29], v[138:141], v[194:197], v[26:29]
	v_mfma_f32_16x16x32_bf16 v[26:29], v[142:145], v[198:201], v[26:29]
	v_mfma_f32_16x16x32_bf16 v[14:17], v[130:133], v[202:205], v[14:17]
	v_mfma_f32_16x16x32_bf16 v[14:17], v[134:137], v[206:209], v[14:17]
	v_mfma_f32_16x16x32_bf16 v[10:13], v[138:141], v[202:205], v[10:13]
	v_mfma_f32_16x16x32_bf16 v[10:13], v[142:145], v[206:209], v[10:13]
	v_mfma_f32_16x16x32_bf16 v[54:57], v[146:149], v[162:165], v[54:57]
	v_mfma_f32_16x16x32_bf16 v[54:57], v[150:153], v[166:169], v[54:57]
	v_mfma_f32_16x16x32_bf16 v[50:53], v[154:157], v[162:165], v[50:53]
	v_mfma_f32_16x16x32_bf16 v[50:53], v[158:161], v[166:169], v[50:53]
	v_mfma_f32_16x16x32_bf16 v[38:41], v[146:149], v[186:189], v[38:41]
	v_mfma_f32_16x16x32_bf16 v[38:41], v[150:153], v[190:193], v[38:41]
	v_mfma_f32_16x16x32_bf16 v[34:37], v[154:157], v[186:189], v[34:37]
	v_mfma_f32_16x16x32_bf16 v[34:37], v[158:161], v[190:193], v[34:37]
	v_mfma_f32_16x16x32_bf16 v[22:25], v[146:149], v[194:197], v[22:25]
	v_mfma_f32_16x16x32_bf16 v[22:25], v[150:153], v[198:201], v[22:25]
	v_mfma_f32_16x16x32_bf16 v[18:21], v[154:157], v[194:197], v[18:21]
	v_mfma_f32_16x16x32_bf16 v[18:21], v[158:161], v[198:201], v[18:21]
	v_mfma_f32_16x16x32_bf16 v[6:9], v[146:149], v[202:205], v[6:9]
	v_mfma_f32_16x16x32_bf16 v[6:9], v[150:153], v[206:209], v[6:9]
	v_mfma_f32_16x16x32_bf16 v[2:5], v[154:157], v[202:205], v[2:5]
	v_mfma_f32_16x16x32_bf16 v[2:5], v[158:161], v[206:209], v[2:5]
	s_barrier
	s_add_i32 s71, s71, 2
	s_add_u32 s69, s69, 0x100
	s_addc_u32 s70, s70, 0
	s_cmpk_gt_u32 s71, 0xdd
	s_mov_b64 s[18:19], s[36:37]
	s_cbranch_scc0 .LBB0_2241
	s_and_b64 vcc, exec, s[10:11]
	s_cbranch_vccz .LBB0_2244
	s_barrier
